# merge GEMM phase also fully LDS-DMA staged; top-read reorder in all GEMM loops where safe
# baseline (speedup 1.0000x reference)
.LBB0_157:
	s_setprio 1
	s_add_u32 s98, s38, s36
	s_addc_u32 s99, s39, 0
	s_add_u32 s98, s98, 0x80
	s_addc_u32 s99, s99, 0
	v_add_u32_e32 v122, v119, v118
	v_add_u32_e32 v124, v119, v120
	v_add_u32_e32 v123, v121, v120
	ds_read_b128 v[126:129], v122 offset:16384
	ds_read_b128 v[130:133], v124
	ds_read_b128 v[144:147], v122 offset:18432
	ds_read_b128 v[158:161], v122 offset:20480
	ds_read_b128 v[162:165], v122 offset:22528
	ds_read_b128 v[134:137], v124 offset:2048
	ds_read_b128 v[140:143], v124 offset:4096
	ds_read_b128 v[148:151], v124 offset:6144
	s_add_u32 m0, s100, 0x8000
	s_waitcnt lgkmcnt(6)
	v_mfma_f32_16x16x32_bf16 v[34:37], v[126:129], v[130:133], v[34:37]
	global_load_lds_dwordx4 v194, s[98:99]
	s_waitcnt lgkmcnt(5)
	v_mfma_f32_16x16x32_bf16 v[94:97], v[144:147], v[130:133], v[94:97]
	ds_read_b128 v[198:201], v123
	s_add_u32 m0, s100, 0xc000
	s_waitcnt lgkmcnt(5)
	v_mfma_f32_16x16x32_bf16 v[38:41], v[158:161], v[130:133], v[38:41]
	global_load_lds_dwordx4 v195, s[98:99]
	s_waitcnt lgkmcnt(4)
	v_mfma_f32_16x16x32_bf16 v[90:93], v[162:165], v[130:133], v[90:93]
	ds_read_b128 v[206:209], v123 offset:2048
	s_add_u32 m0, s100, 0x9000
	s_waitcnt lgkmcnt(4)
	v_mfma_f32_16x16x32_bf16 v[42:45], v[126:129], v[134:137], v[42:45]
	global_load_lds_dwordx4 v196, s[98:99]
	v_mfma_f32_16x16x32_bf16 v[86:89], v[144:147], v[134:137], v[86:89]
	ds_read_b128 v[214:217], v123 offset:4096
	s_add_u32 m0, s100, 0xd000
	v_mfma_f32_16x16x32_bf16 v[46:49], v[158:161], v[134:137], v[46:49]
	global_load_lds_dwordx4 v197, s[98:99]
	v_mfma_f32_16x16x32_bf16 v[82:85], v[162:165], v[134:137], v[82:85]
	v_add_u32_e32 v130, v121, v118
	ds_read_b128 v[132:135], v123 offset:6144
	s_add_u32 m0, s100, 0xa000
	s_waitcnt lgkmcnt(5)
	v_mfma_f32_16x16x32_bf16 v[50:53], v[126:129], v[140:143], v[50:53]
	global_load_lds_dwordx4 v202, s[98:99]
	v_mfma_f32_16x16x32_bf16 v[78:81], v[144:147], v[140:143], v[78:81]
	ds_read_b128 v[226:229], v130 offset:16384
	s_add_u32 m0, s100, 0xe000
	v_mfma_f32_16x16x32_bf16 v[54:57], v[158:161], v[140:143], v[54:57]
	global_load_lds_dwordx4 v203, s[98:99]
	v_mfma_f32_16x16x32_bf16 v[70:73], v[162:165], v[140:143], v[70:73]
	ds_read_b128 v[140:143], v130 offset:18432
	s_add_u32 m0, s100, 0xb000
	s_waitcnt lgkmcnt(6)
	v_mfma_f32_16x16x32_bf16 v[58:61], v[126:129], v[148:151], v[58:61]
	global_load_lds_dwordx4 v204, s[98:99]
	v_mfma_f32_16x16x32_bf16 v[66:69], v[144:147], v[148:151], v[66:69]
	ds_read_b128 v[144:147], v130 offset:20480
	s_add_u32 m0, s100, 0xf000
	v_mfma_f32_16x16x32_bf16 v[62:65], v[158:161], v[148:151], v[62:65]
	global_load_lds_dwordx4 v205, s[98:99]
	v_mfma_f32_16x16x32_bf16 v[74:77], v[162:165], v[148:151], v[74:77]
	ds_read_b128 v[148:151], v130 offset:22528
	s_waitcnt lgkmcnt(3)
	v_mfma_f32_16x16x32_bf16 v[34:37], v[226:229], v[198:201], v[34:37]
	s_waitcnt lgkmcnt(2)
	v_mfma_f32_16x16x32_bf16 v[94:97], v[140:143], v[198:201], v[94:97]
	s_waitcnt lgkmcnt(1)
	v_mfma_f32_16x16x32_bf16 v[38:41], v[144:147], v[198:201], v[38:41]
	s_waitcnt lgkmcnt(0)
	v_mfma_f32_16x16x32_bf16 v[90:93], v[148:151], v[198:201], v[90:93]
	v_mfma_f32_16x16x32_bf16 v[42:45], v[226:229], v[206:209], v[42:45]
	v_mfma_f32_16x16x32_bf16 v[86:89], v[140:143], v[206:209], v[86:89]
	v_mfma_f32_16x16x32_bf16 v[46:49], v[144:147], v[206:209], v[46:49]
	v_mfma_f32_16x16x32_bf16 v[82:85], v[148:151], v[206:209], v[82:85]
	v_mfma_f32_16x16x32_bf16 v[50:53], v[226:229], v[214:217], v[50:53]
	v_mfma_f32_16x16x32_bf16 v[78:81], v[140:143], v[214:217], v[78:81]
	v_mfma_f32_16x16x32_bf16 v[54:57], v[144:147], v[214:217], v[54:57]
	v_mfma_f32_16x16x32_bf16 v[70:73], v[148:151], v[214:217], v[70:73]
	v_mfma_f32_16x16x32_bf16 v[58:61], v[226:229], v[132:135], v[58:61]
	v_mfma_f32_16x16x32_bf16 v[66:69], v[140:143], v[132:135], v[66:69]
	v_mfma_f32_16x16x32_bf16 v[62:65], v[144:147], v[132:135], v[62:65]
	v_mfma_f32_16x16x32_bf16 v[74:77], v[148:151], v[132:135], v[74:77]
	s_waitcnt vmcnt(0)
	s_setprio 0
	s_waitcnt lgkmcnt(0)
	s_barrier
	s_setprio 1
	s_add_u32 s98, s98, 0x80
	s_addc_u32 s99, s99, 0
	ds_read_b128 v[26:29], v122 offset:49152
	ds_read_b128 v[10:13], v124 offset:32768
	ds_read_b128 v[30:33], v122 offset:51200
	ds_read_b128 v[144:147], v122 offset:53248
	ds_read_b128 v[148:151], v122 offset:55296
	ds_read_b128 v[18:21], v124 offset:34816
	ds_read_b128 v[132:135], v124 offset:36864
	ds_read_b128 v[140:143], v124 offset:38912
	s_add_u32 m0, s100, 0x0
	s_waitcnt lgkmcnt(6)
	v_mfma_f32_16x16x32_bf16 v[34:37], v[26:29], v[10:13], v[34:37]
	global_load_lds_dwordx4 v194, s[98:99]
	s_waitcnt lgkmcnt(5)
	v_mfma_f32_16x16x32_bf16 v[94:97], v[30:33], v[10:13], v[94:97]
	ds_read_b128 v[162:165], v123 offset:32768
	s_add_u32 m0, s100, 0x4000
	s_waitcnt lgkmcnt(5)
	v_mfma_f32_16x16x32_bf16 v[38:41], v[144:147], v[10:13], v[38:41]
	global_load_lds_dwordx4 v195, s[98:99]
	s_waitcnt lgkmcnt(4)
	v_mfma_f32_16x16x32_bf16 v[90:93], v[148:151], v[10:13], v[90:93]
	ds_read_b128 v[198:201], v123 offset:34816
	s_add_u32 m0, s100, 0x1000
	s_waitcnt lgkmcnt(4)
	v_mfma_f32_16x16x32_bf16 v[42:45], v[26:29], v[18:21], v[42:45]
	global_load_lds_dwordx4 v196, s[98:99]
	v_mfma_f32_16x16x32_bf16 v[86:89], v[30:33], v[18:21], v[86:89]
	ds_read_b128 v[206:209], v123 offset:36864
	s_add_u32 m0, s100, 0x5000
	v_mfma_f32_16x16x32_bf16 v[46:49], v[144:147], v[18:21], v[46:49]
	global_load_lds_dwordx4 v197, s[98:99]
	v_mfma_f32_16x16x32_bf16 v[82:85], v[148:151], v[18:21], v[82:85]
	ds_read_b128 v[214:217], v123 offset:38912
	s_add_u32 m0, s100, 0x2000
	s_waitcnt lgkmcnt(5)
	v_mfma_f32_16x16x32_bf16 v[50:53], v[26:29], v[132:135], v[50:53]
	global_load_lds_dwordx4 v202, s[98:99]
	v_mfma_f32_16x16x32_bf16 v[78:81], v[30:33], v[132:135], v[78:81]
	ds_read_b128 v[226:229], v130 offset:49152
	s_add_u32 m0, s100, 0x6000
	v_mfma_f32_16x16x32_bf16 v[54:57], v[144:147], v[132:135], v[54:57]
	global_load_lds_dwordx4 v203, s[98:99]
	v_mfma_f32_16x16x32_bf16 v[70:73], v[148:151], v[132:135], v[70:73]
	ds_read_b128 v[132:135], v130 offset:51200
	s_add_u32 m0, s100, 0x3000
	s_waitcnt lgkmcnt(6)
	v_mfma_f32_16x16x32_bf16 v[58:61], v[26:29], v[140:143], v[58:61]
	global_load_lds_dwordx4 v204, s[98:99]
	v_mfma_f32_16x16x32_bf16 v[66:69], v[30:33], v[140:143], v[66:69]
	ds_read_b128 v[234:237], v130 offset:53248
	s_add_u32 m0, s100, 0x7000
	v_mfma_f32_16x16x32_bf16 v[62:65], v[144:147], v[140:143], v[62:65]
	global_load_lds_dwordx4 v205, s[98:99]
	v_mfma_f32_16x16x32_bf16 v[74:77], v[148:151], v[140:143], v[74:77]
	ds_read_b128 v[140:143], v130 offset:55296
	s_waitcnt lgkmcnt(3)
	v_mfma_f32_16x16x32_bf16 v[34:37], v[226:229], v[162:165], v[34:37]
	s_waitcnt lgkmcnt(2)
	v_mfma_f32_16x16x32_bf16 v[94:97], v[132:135], v[162:165], v[94:97]
	s_waitcnt lgkmcnt(1)
	v_mfma_f32_16x16x32_bf16 v[38:41], v[234:237], v[162:165], v[38:41]
	s_waitcnt lgkmcnt(0)
	v_mfma_f32_16x16x32_bf16 v[90:93], v[140:143], v[162:165], v[90:93]
	v_mfma_f32_16x16x32_bf16 v[42:45], v[226:229], v[198:201], v[42:45]
	v_mfma_f32_16x16x32_bf16 v[86:89], v[132:135], v[198:201], v[86:89]
	v_mfma_f32_16x16x32_bf16 v[46:49], v[234:237], v[198:201], v[46:49]
	v_mfma_f32_16x16x32_bf16 v[82:85], v[140:143], v[198:201], v[82:85]
	v_mfma_f32_16x16x32_bf16 v[50:53], v[226:229], v[206:209], v[50:53]
	v_mfma_f32_16x16x32_bf16 v[78:81], v[132:135], v[206:209], v[78:81]
	v_mfma_f32_16x16x32_bf16 v[54:57], v[234:237], v[206:209], v[54:57]
	v_mfma_f32_16x16x32_bf16 v[70:73], v[140:143], v[206:209], v[70:73]
	v_mfma_f32_16x16x32_bf16 v[58:61], v[226:229], v[214:217], v[58:61]
	v_mfma_f32_16x16x32_bf16 v[66:69], v[132:135], v[214:217], v[66:69]
	v_mfma_f32_16x16x32_bf16 v[62:65], v[234:237], v[214:217], v[62:65]
	v_mfma_f32_16x16x32_bf16 v[74:77], v[140:143], v[214:217], v[74:77]
	s_waitcnt vmcnt(0)
	s_setprio 0
	s_add_i32 s5, s5, 2
	s_add_u32 s38, s38, 0x100
	s_addc_u32 s39, s39, 0
	s_cmp_lt_u32 s5, 12
	s_waitcnt lgkmcnt(0)
	s_barrier
	s_cbranch_scc1 .LBB0_157
	v_mov_b32_e32 v2, v194
	v_mov_b32_e32 v3, v195
	v_mov_b32_e32 v4, v196
	v_mov_b32_e32 v5, v197
	v_mov_b32_e32 v6, v202
	v_mov_b32_e32 v7, v203
	v_mov_b32_e32 v8, v204
	v_mov_b32_e32 v9, v205
	s_add_u32 s98, s38, s36
	s_addc_u32 s99, s39, 0
	s_add_u32 s98, s98, 0x80
	s_addc_u32 s99, s99, 0
	s_add_i32 s5, s11, s2
	s_cmpk_lt_u32 s5, 0x100
	s_cselect_b64 s[44:45], -1, 0
	s_and_b64 s[8:9], s[44:45], exec
	s_cselect_b32 s9, s5, s11
	s_lshr_b32 s8, s9, 3
	s_and_b32 s8, s8, 0x1fffff8
	s_add_i32 s8, s8, s21
	s_and_b32 s11, s9, 7
	v_mov_b32_e32 v0, v169
	s_or_b32 s8, s8, s11
	s_lshl_b32 s8, s8, 7
	v_lshrrev_b32_e32 v98, 3, v0
	v_lshlrev_b32_e32 v0, 3, v0
	v_add_u32_e32 v98, s8, v98
	v_and_b32_e32 v0, 56, v0
	v_lshl_or_b32 v0, v98, 10, v0
	v_mov_b32_e32 v98, v169
	s_lshl_b32 s9, s9, 4
	s_and_b32 s9, s9, 0x380
	v_lshrrev_b32_e32 v99, 3, v98
	v_lshlrev_b32_e32 v98, 3, v98
	v_add_u32_e32 v99, s9, v99
	v_and_b32_e32 v98, 56, v98
	v_add_u32_e32 v114, 0x8000, v0
	v_add_u32_e32 v136, 0x10000, v0
	v_lshl_or_b32 v162, v99, 10, v98
	v_add_u32_e32 v166, 0x18000, v0
	v_add_u32_e32 v174, 0x8000, v162
	v_add_u32_e32 v176, 0x10000, v162
	v_add_u32_e32 v178, 0x18000, v162
	s_setprio 1
	ds_read_b128 v[98:101], v122 offset:16384
	ds_read_b128 v[102:105], v124
	ds_read_b128 v[110:113], v122 offset:18432
	ds_read_b128 v[132:135], v122 offset:20480
	ds_read_b128 v[140:143], v122 offset:22528
	ds_read_b128 v[106:109], v124 offset:2048
	ds_read_b128 v[118:121], v124 offset:4096
	ds_read_b128 v[126:129], v124 offset:6144
	v_lshrrev_b32_e32 v14, 3, v169
	v_and_b32_e32 v15, 3, v14
	v_bfe_u32 v16, v14, 4, 1
	v_lshl_or_b32 v15, v16, 2, v15
	v_bfe_u32 v16, v14, 2, 1
	v_lshl_or_b32 v15, v16, 3, v15
	v_bfe_u32 v16, v14, 3, 1
	v_lshl_or_b32 v15, v16, 4, v15
	v_sub_u32_e32 v15, v15, v14
	v_mul_i32_i24_e32 v15, 0x400, v15
	v_and_b32_e32 v14, 7, v14
	v_lshlrev_b32_e32 v14, 3, v14
	v_xor_b32_e32 v0, v0, v14
	v_add_u32_e32 v162, v162, v15
	v_xor_b32_e32 v162, v162, v14
	v_xor_b32_e32 v114, v114, v14
	v_add_u32_e32 v174, v174, v15
	v_xor_b32_e32 v174, v174, v14
	v_xor_b32_e32 v136, v136, v14
	v_add_u32_e32 v176, v176, v15
	v_xor_b32_e32 v176, v176, v14
	v_xor_b32_e32 v166, v166, v14
	v_add_u32_e32 v178, v178, v15
	v_xor_b32_e32 v178, v178, v14
	v_readlane_b32 s14, v254, 45
	v_readlane_b32 s15, v254, 46
	v_mov_b32_e32 v163, v1
	v_mov_b32_e32 v115, v1
	v_mov_b32_e32 v175, v1
	v_mov_b32_e32 v137, v1
	v_mov_b32_e32 v177, v1
	v_mov_b32_e32 v167, v1
	v_mov_b32_e32 v179, v1
	v_lshl_add_u64 v[180:181], v[0:1], 1, s[14:15]
	v_lshl_add_u64 v[186:187], v[162:163], 1, s[34:35]
	v_lshl_add_u64 v[188:189], v[114:115], 1, s[14:15]
	v_lshl_add_u64 v[174:175], v[174:175], 1, s[34:35]
	v_lshl_add_u64 v[136:137], v[136:137], 1, s[14:15]
	v_lshl_add_u64 v[176:177], v[176:177], 1, s[34:35]
	v_lshl_add_u64 v[166:167], v[166:167], 1, s[14:15]
	v_lshl_add_u64 v[178:179], v[178:179], 1, s[34:35]
	s_add_u32 m0, s100, 0x8000
	s_waitcnt lgkmcnt(6)
	v_mfma_f32_16x16x32_bf16 v[144:147], v[98:101], v[102:105], v[34:37]
	global_load_lds_dwordx4 v2, s[98:99]
	s_waitcnt lgkmcnt(5)
	v_mfma_f32_16x16x32_bf16 v[94:97], v[110:113], v[102:105], v[94:97]
	ds_read_b128 v[148:151], v123
	s_add_u32 m0, s100, 0xc000
	s_waitcnt lgkmcnt(5)
	v_mfma_f32_16x16x32_bf16 v[158:161], v[132:135], v[102:105], v[38:41]
	global_load_lds_dwordx4 v3, s[98:99]
	s_waitcnt lgkmcnt(4)
	v_mfma_f32_16x16x32_bf16 v[90:93], v[140:143], v[102:105], v[90:93]
	ds_read_b128 v[102:105], v123 offset:2048
	s_add_u32 m0, s100, 0x9000
	s_waitcnt lgkmcnt(4)
	v_mfma_f32_16x16x32_bf16 v[162:165], v[98:101], v[106:109], v[42:45]
	global_load_lds_dwordx4 v4, s[98:99]
	v_mfma_f32_16x16x32_bf16 v[86:89], v[110:113], v[106:109], v[86:89]
	ds_read_b128 v[194:197], v123 offset:4096
	s_add_u32 m0, s100, 0xd000
	v_mfma_f32_16x16x32_bf16 v[198:201], v[132:135], v[106:109], v[46:49]
	global_load_lds_dwordx4 v5, s[98:99]
	v_mfma_f32_16x16x32_bf16 v[82:85], v[140:143], v[106:109], v[82:85]
	ds_read_b128 v[106:109], v123 offset:6144
	s_add_u32 m0, s100, 0xa000
	s_waitcnt lgkmcnt(5)
	v_mfma_f32_16x16x32_bf16 v[202:205], v[98:101], v[118:121], v[50:53]
	global_load_lds_dwordx4 v6, s[98:99]
	v_mfma_f32_16x16x32_bf16 v[78:81], v[110:113], v[118:121], v[78:81]
	ds_read_b128 v[206:209], v130 offset:16384
	s_add_u32 m0, s100, 0xe000
	v_mfma_f32_16x16x32_bf16 v[210:213], v[132:135], v[118:121], v[54:57]
	global_load_lds_dwordx4 v7, s[98:99]
	v_mfma_f32_16x16x32_bf16 v[70:73], v[140:143], v[118:121], v[70:73]
	ds_read_b128 v[118:121], v130 offset:18432
	s_add_u32 m0, s100, 0xb000
	s_waitcnt lgkmcnt(6)
	v_mfma_f32_16x16x32_bf16 v[98:101], v[98:101], v[126:129], v[58:61]
	global_load_lds_dwordx4 v8, s[98:99]
	v_mfma_f32_16x16x32_bf16 v[66:69], v[110:113], v[126:129], v[66:69]
	ds_read_b128 v[110:113], v130 offset:20480
	s_add_u32 m0, s100, 0xf000
	v_mfma_f32_16x16x32_bf16 v[132:135], v[132:135], v[126:129], v[62:65]
	global_load_lds_dwordx4 v9, s[98:99]
	v_mfma_f32_16x16x32_bf16 v[74:77], v[140:143], v[126:129], v[74:77]
	ds_read_b128 v[126:129], v130 offset:22528
	s_waitcnt lgkmcnt(3)
	v_mfma_f32_16x16x32_bf16 v[140:143], v[206:209], v[148:151], v[144:147]
	s_waitcnt lgkmcnt(2)
	v_mfma_f32_16x16x32_bf16 v[94:97], v[118:121], v[148:151], v[94:97]
	s_waitcnt lgkmcnt(1)
	v_mfma_f32_16x16x32_bf16 v[144:147], v[110:113], v[148:151], v[158:161]
	s_waitcnt lgkmcnt(0)
	v_mfma_f32_16x16x32_bf16 v[90:93], v[126:129], v[148:151], v[90:93]
	v_mfma_f32_16x16x32_bf16 v[148:151], v[206:209], v[102:105], v[162:165]
	v_mfma_f32_16x16x32_bf16 v[86:89], v[118:121], v[102:105], v[86:89]
	v_mfma_f32_16x16x32_bf16 v[158:161], v[110:113], v[102:105], v[198:201]
	v_mfma_f32_16x16x32_bf16 v[82:85], v[126:129], v[102:105], v[82:85]
	v_mfma_f32_16x16x32_bf16 v[102:105], v[206:209], v[194:197], v[202:205]
	v_mfma_f32_16x16x32_bf16 v[78:81], v[118:121], v[194:197], v[78:81]
	v_mfma_f32_16x16x32_bf16 v[162:165], v[110:113], v[194:197], v[210:213]
	v_mfma_f32_16x16x32_bf16 v[70:73], v[126:129], v[194:197], v[70:73]
	v_mfma_f32_16x16x32_bf16 v[98:101], v[206:209], v[106:109], v[98:101]
	v_mfma_f32_16x16x32_bf16 v[66:69], v[118:121], v[106:109], v[66:69]
	v_mfma_f32_16x16x32_bf16 v[110:113], v[110:113], v[106:109], v[132:135]
	v_mfma_f32_16x16x32_bf16 v[74:77], v[126:129], v[106:109], v[74:77]
	s_waitcnt vmcnt(0)
	s_setprio 0
	s_waitcnt lgkmcnt(0)
	s_barrier
	s_setprio 1
	ds_read_b128 v[26:29], v122 offset:49152
	ds_read_b128 v[10:13], v124 offset:32768
	ds_read_b128 v[18:21], v124 offset:34816
	ds_read_b128 v[30:33], v122 offset:51200
	ds_read_b128 v[106:109], v124 offset:36864
	ds_read_b128 v[114:117], v124 offset:38912
	ds_read_b128 v[118:121], v122 offset:53248
	ds_read_b128 v[124:127], v122 offset:55296
	s_add_u32 m0, s100, 0x0
	s_waitcnt lgkmcnt(6)
	v_mfma_f32_16x16x32_bf16 v[132:135], v[26:29], v[10:13], v[140:143]
	global_load_lds_dwordx4 v[180:181], off
	s_waitcnt lgkmcnt(4)
	v_mfma_f32_16x16x32_bf16 v[94:97], v[30:33], v[10:13], v[94:97]
	ds_read_b128 v[140:143], v123 offset:32768
	s_add_u32 m0, s100, 0x4000
	s_waitcnt lgkmcnt(2)
	v_mfma_f32_16x16x32_bf16 v[144:147], v[118:121], v[10:13], v[144:147]
	global_load_lds_dwordx4 v[186:187], off
	s_waitcnt lgkmcnt(1)
	v_mfma_f32_16x16x32_bf16 v[90:93], v[124:127], v[10:13], v[90:93]
	ds_read_b128 v[194:197], v123 offset:34816
	s_add_u32 m0, s100, 0x1000
	v_mfma_f32_16x16x32_bf16 v[148:151], v[26:29], v[18:21], v[148:151]
	global_load_lds_dwordx4 v[188:189], off
	v_mfma_f32_16x16x32_bf16 v[86:89], v[30:33], v[18:21], v[86:89]
	ds_read_b128 v[198:201], v123 offset:36864
	s_add_u32 m0, s100, 0x5000
	v_mfma_f32_16x16x32_bf16 v[158:161], v[118:121], v[18:21], v[158:161]
	global_load_lds_dwordx4 v[174:175], off
	v_mfma_f32_16x16x32_bf16 v[82:85], v[124:127], v[18:21], v[82:85]
	ds_read_b128 v[202:205], v123 offset:38912
	s_add_u32 m0, s100, 0x2000
	v_mfma_f32_16x16x32_bf16 v[206:209], v[26:29], v[106:109], v[102:105]
	global_load_lds_dwordx4 v[136:137], off
	v_mfma_f32_16x16x32_bf16 v[78:81], v[30:33], v[106:109], v[78:81]
	ds_read_b128 v[210:213], v130 offset:49152
	s_add_u32 m0, s100, 0x6000
	v_mfma_f32_16x16x32_bf16 v[162:165], v[118:121], v[106:109], v[162:165]
	global_load_lds_dwordx4 v[176:177], off
	v_mfma_f32_16x16x32_bf16 v[70:73], v[124:127], v[106:109], v[70:73]
	ds_read_b128 v[214:217], v130 offset:51200
	s_add_u32 m0, s100, 0x3000
	v_mfma_f32_16x16x32_bf16 v[218:221], v[26:29], v[114:117], v[98:101]
	global_load_lds_dwordx4 v[166:167], off
	v_mfma_f32_16x16x32_bf16 v[66:69], v[30:33], v[114:117], v[66:69]
	ds_read_b128 v[222:225], v130 offset:53248
	s_add_u32 m0, s100, 0x7000
	v_mfma_f32_16x16x32_bf16 v[226:229], v[118:121], v[114:117], v[110:113]
	global_load_lds_dwordx4 v[178:179], off
	v_mfma_f32_16x16x32_bf16 v[230:233], v[124:127], v[114:117], v[74:77]
	s_waitcnt lgkmcnt(2)
	v_mfma_f32_16x16x32_bf16 v[126:129], v[210:213], v[140:143], v[132:135]
	ds_read_b128 v[130:133], v130 offset:55296
	s_waitcnt lgkmcnt(2)
	v_mfma_f32_16x16x32_bf16 v[122:125], v[214:217], v[140:143], v[94:97]
	s_waitcnt lgkmcnt(1)
	v_mfma_f32_16x16x32_bf16 v[118:121], v[222:225], v[140:143], v[144:147]
	s_waitcnt lgkmcnt(0)
	v_mfma_f32_16x16x32_bf16 v[114:117], v[130:133], v[140:143], v[90:93]
	v_mfma_f32_16x16x32_bf16 v[110:113], v[210:213], v[194:197], v[148:151]
	v_mfma_f32_16x16x32_bf16 v[106:109], v[214:217], v[194:197], v[86:89]
	v_mfma_f32_16x16x32_bf16 v[102:105], v[222:225], v[194:197], v[158:161]
	v_mfma_f32_16x16x32_bf16 v[98:101], v[130:133], v[194:197], v[82:85]
	v_mfma_f32_16x16x32_bf16 v[94:97], v[210:213], v[198:201], v[206:209]
	v_mfma_f32_16x16x32_bf16 v[90:93], v[214:217], v[198:201], v[78:81]
	v_mfma_f32_16x16x32_bf16 v[86:89], v[222:225], v[198:201], v[162:165]
	v_mfma_f32_16x16x32_bf16 v[82:85], v[130:133], v[198:201], v[70:73]
	v_mfma_f32_16x16x32_bf16 v[78:81], v[210:213], v[202:205], v[218:221]
	v_mfma_f32_16x16x32_bf16 v[74:77], v[214:217], v[202:205], v[66:69]
	v_mfma_f32_16x16x32_bf16 v[70:73], v[222:225], v[202:205], v[226:229]
	v_mfma_f32_16x16x32_bf16 v[66:69], v[130:133], v[202:205], v[230:233]
	s_setprio 0
	v_add_u32_e32 v134, s4, v152
	v_ashrrev_i32_e32 v135, 31, v134
	v_lshlrev_b64 v[136:137], 12, v[134:135]
	v_or_b32_e32 v140, s10, v153
	v_mov_b32_e32 v141, v1
	v_cndmask_b32_e64 v0, 0, 1, s[42:43]
	v_lshl_add_u64 v[130:131], s[40:41], 0, v[136:137]
	v_cmp_ne_u32_e64 s[38:39], 1, v0
	s_andn2_b64 vcc, exec, s[42:43]
	v_lshl_add_u64 v[146:147], v[140:141], 2, v[130:131]
	s_barrier
	s_cbranch_vccnz .LBB0_160
	global_load_dwordx4 v[130:133], v[146:147], off
	s_mov_b64 s[46:47], 0
	s_branch .LBB0_161

.LBB0_229:
	s_andn2_b64 vcc, exec, s[0:1]
	s_cbranch_vccnz .LBB0_668
	v_readlane_b32 s0, v255, 36
	v_readlane_b32 s1, v255, 37
	s_lshl_b32 s0, s0, 2
	s_ashr_i32 s1, s0, 31
	v_writelane_b32 v255, s0, 38
	s_cmp_lt_i32 s25, 2
	s_mov_b32 s91, s65
	v_writelane_b32 v255, s1, 39
	v_writelane_b32 v255, s25, 40
	s_mov_b64 s[0:1], -1
	s_cbranch_scc1 .LBB0_406
	v_readlane_b32 s0, v255, 40
	s_cmp_gt_i32 s0, 2
	s_mov_b64 s[0:1], -1
	s_cbranch_scc0 .LBB0_313
	v_readlane_b32 s4, v254, 37
	v_readlane_b32 s5, v254, 38
	s_mov_b64 s[0:1], 0
	v_mov_b32_e32 v80, v169
	s_andn2_b64 vcc, exec, s[4:5]
	s_cbranch_vccnz .LBB0_312
	v_readlane_b32 s4, v255, 36
	v_readlane_b32 s5, v255, 37
	s_lshl_b64 s[28:29], s[4:5], 22
	s_lshl_b64 s[4:5], s[4:5], 20
	s_add_u32 s2, s72, s0
	s_addc_u32 s8, s73, s1
	s_add_u32 s0, s2, 0x4991000
	s_addc_u32 s1, s8, 0
	s_add_u32 s38, s2, 0x8991000
	s_addc_u32 s39, s8, 0
	s_add_u32 s40, s2, 0xa991000
	s_addc_u32 s41, s8, 0
	s_add_u32 s4, s2, s4
	s_addc_u32 s5, s8, s5
	v_mov_b32_e32 v0, v169
	s_add_u32 s42, s4, 0x1880000
	s_load_dword s4, s[22:23], 0x0
	v_readlane_b32 s14, v254, 39
	s_waitcnt vmcnt(7)
	v_lshrrev_b32_e32 v2, 3, v0
	v_lshlrev_b32_e32 v0, 3, v0
	v_add_u32_e32 v2, s14, v2
	v_and_b32_e32 v0, 56, v0
	v_lshl_or_b32 v0, v2, 9, v0
	v_mov_b32_e32 v2, v169
	v_readlane_b32 s15, v254, 40
	v_lshrrev_b32_e32 v3, 3, v2
	v_lshlrev_b32_e32 v2, 3, v2
	v_add_u32_e32 v3, s15, v3
	v_and_b32_e32 v2, 56, v2
	v_lshl_or_b32 v78, v3, 9, v2
	s_addc_u32 s43, s5, 0
	v_add_u32_e32 v70, 0x4000, v0
	v_add_u32_e32 v68, 0x8000, v0
	s_waitcnt lgkmcnt(0)
	v_add_u32_e32 v66, 0xc000, v0
	v_add_u32_e32 v76, 0x4000, v78
	v_add_u32_e32 v74, 0x8000, v78
	v_add_u32_e32 v72, 0xc000, v78
	v_mov_b32_e32 v79, v1
	v_mov_b32_e32 v71, v1
	v_mov_b32_e32 v77, v1
	v_mov_b32_e32 v69, v1
	v_mov_b32_e32 v75, v1
	v_mov_b32_e32 v67, v1
	v_mov_b32_e32 v73, v1
	v_lshl_add_u64 v[2:3], v[0:1], 1, s[38:39]
	s_waitcnt vmcnt(6)
	v_lshl_add_u64 v[6:7], v[78:79], 1, s[42:43]
	s_waitcnt vmcnt(5)
	v_lshl_add_u64 v[10:11], v[70:71], 1, s[38:39]
	s_waitcnt vmcnt(4)
	v_lshl_add_u64 v[14:15], v[76:77], 1, s[42:43]
	s_waitcnt vmcnt(3)
	v_lshl_add_u64 v[18:19], v[68:69], 1, s[38:39]
	s_waitcnt vmcnt(2)
	v_lshl_add_u64 v[22:23], v[74:75], 1, s[42:43]
	s_waitcnt vmcnt(1)
	v_lshl_add_u64 v[26:27], v[66:67], 1, s[38:39]
	s_waitcnt vmcnt(0)
	v_lshl_add_u64 v[30:31], v[72:73], 1, s[42:43]
	s_movk_i32 s101, 0x200
	v_lshrrev_b32_e32 v34, 6, v169
	v_lshlrev_b32_e32 v34, 10, v34
	s_nop 0
	v_readfirstlane_b32 s100, v34
	v_lshrrev_b32_e32 v35, 3, v169
	v_and_b32_e32 v36, 3, v35
	v_bfe_u32 v37, v35, 4, 1
	v_lshl_or_b32 v36, v37, 2, v36
	v_bfe_u32 v37, v35, 2, 1
	v_lshl_or_b32 v36, v37, 3, v36
	v_bfe_u32 v37, v35, 3, 1
	v_lshl_or_b32 v36, v37, 4, v36
	v_sub_u32_e32 v36, v36, v35
	v_and_b32_e32 v35, 7, v35
	v_mul_i32_i24_e32 v36, 0x400, v36
	v_lshlrev_b32_e32 v35, 4, v35
	v_ashrrev_i32_e32 v37, 31, v36
	v_xor_b32_e32 v2, v2, v35
	v_lshl_add_u64 v[6:7], v[6:7], 0, v[36:37]
	v_xor_b32_e32 v6, v6, v35
	v_xor_b32_e32 v10, v10, v35
	v_lshl_add_u64 v[14:15], v[14:15], 0, v[36:37]
	v_xor_b32_e32 v14, v14, v35
	v_xor_b32_e32 v18, v18, v35
	v_lshl_add_u64 v[22:23], v[22:23], 0, v[36:37]
	v_xor_b32_e32 v22, v22, v35
	v_xor_b32_e32 v26, v26, v35
	v_lshl_add_u64 v[30:31], v[30:31], 0, v[36:37]
	v_xor_b32_e32 v30, v30, v35
	s_add_u32 m0, s100, 0x0
	s_nop 0
	global_load_lds_dwordx4 v[2:3], off
	s_add_u32 m0, s100, 0x4000
	s_nop 0
	global_load_lds_dwordx4 v[6:7], off
	s_add_u32 m0, s100, 0x1000
	s_nop 0
	global_load_lds_dwordx4 v[10:11], off
	s_add_u32 m0, s100, 0x5000
	s_nop 0
	global_load_lds_dwordx4 v[14:15], off
	s_add_u32 m0, s100, 0x2000
	s_nop 0
	global_load_lds_dwordx4 v[18:19], off
	s_add_u32 m0, s100, 0x6000
	s_nop 0
	global_load_lds_dwordx4 v[22:23], off
	s_add_u32 m0, s100, 0x3000
	s_nop 0
	global_load_lds_dwordx4 v[26:27], off
	s_add_u32 m0, s100, 0x7000
	s_nop 0
	global_load_lds_dwordx4 v[30:31], off
	s_waitcnt vmcnt(0)
	s_add_u32 s5, s2, s28
	s_addc_u32 s9, s8, s29
	s_add_u32 s44, s5, 0x1080000
	s_addc_u32 s45, s9, 0
	s_add_u32 s46, s2, 0x10991000
	v_and_b32_e32 v69, 15, v80
	v_ashrrev_i32_e32 v71, 1, v80
	s_movk_i32 s2, 0xffc0
	v_and_b32_e32 v67, 64, v80
	v_and_or_b32 v146, v71, s2, v69
	v_lshrrev_b32_e32 v69, 1, v80
	s_addc_u32 s47, s8, 0
	s_waitcnt lgkmcnt(0)
	s_lshr_b32 s8, s4, 3
	v_and_or_b32 v147, v69, 24, v67
	v_or_b32_e32 v148, 16, v146
	v_or_b32_e32 v149, 32, v146
	v_or_b32_e32 v150, 48, v146
	s_mov_b32 s10, 0
	v_mov_b32_e32 v116, 6
	s_mov_b64 s[28:29], s[42:43]
	s_mov_b64 s[34:35], s[38:39]
	v_readlane_b32 s11, v254, 57
	s_branch .LBB0_236

.LBB0_236:
	v_mov_b32_e32 v67, v169
	s_mov_b32 s4, s11
	v_lshrrev_b32_e32 v69, 4, v67
	v_ashrrev_i32_e32 v71, 3, v67
	v_lshrrev_b32_e32 v77, 1, v67
	v_and_b32_e32 v80, 4, v69
	v_and_b32_e32 v81, 3, v71
	v_and_b32_e32 v73, 7, v67
	v_xor_b32_e32 v75, v71, v67
	v_and_b32_e32 v77, 16, v77
	v_and_b32_e32 v79, 8, v69
	v_or_b32_e32 v82, v80, v81
	v_lshlrev_b32_e32 v75, 4, v75
	v_or3_b32 v77, v77, v79, v82
	v_bitop3_b32 v79, v80, v73, v81 bitop3:0x36
	v_lshlrev_b32_e32 v71, 7, v71
	v_lshlrev_b32_e32 v79, 4, v79
	v_and_or_b32 v115, v75, s24, v71
	v_lshl_or_b32 v114, v77, 7, v79
	v_lshlrev_b32_e32 v34, 7, v67
	v_and_b32_e32 v35, 0x780, v34
	v_and_b32_e32 v120, 0x2780, v34
	v_bitop3_b32 v34, v69, v73, 3 bitop3:0x6c
	v_bfe_u32 v77, v67, 4, 2
	v_lshlrev_b32_e32 v121, 4, v34
	v_lshlrev_b32_e32 v34, 6, v67
	v_mov_b32_e32 v75, v1
	v_and_or_b32 v122, v34, s30, v35
	v_bitop3_b32 v34, v77, v73, 4 bitop3:0x36
	v_mov_b32_e32 v79, v1
	v_mov_b32_e32 v71, v1
	v_mov_b32_e32 v77, v1
	v_mov_b32_e32 v69, v1
	v_lshl_add_u64 v[108:109], v[74:75], 1, s[28:29]
	v_mov_b32_e32 v67, v1
	v_mov_b32_e32 v73, v1
	v_mov_b32_e32 v74, 0
	s_mov_b32 s9, s10
	s_mov_b32 s2, s15
	s_mov_b32 s25, s14
	v_lshlrev_b32_e32 v123, 4, v34
	v_lshl_add_u64 v[98:99], v[0:1], 1, s[34:35]
	v_lshl_add_u64 v[100:101], v[78:79], 1, s[28:29]
	v_lshl_add_u64 v[102:103], v[70:71], 1, s[34:35]
	v_lshl_add_u64 v[104:105], v[76:77], 1, s[28:29]
	v_lshl_add_u64 v[106:107], v[68:69], 1, s[34:35]
	v_lshl_add_u64 v[110:111], v[66:67], 1, s[34:35]
	v_lshl_add_u64 v[112:113], v[72:73], 1, s[28:29]
	v_lshrrev_b32_e32 v223, 6, v169
	v_lshlrev_b32_e32 v223, 10, v223
	s_lshl_b32 s99, s101, 1
	v_readfirstlane_b32 s100, v223
	v_lshrrev_b32_e32 v222, 3, v169
	v_and_b32_e32 v224, 3, v222
	v_bfe_u32 v223, v222, 4, 1
	v_lshl_or_b32 v224, v223, 2, v224
	v_bfe_u32 v223, v222, 2, 1
	v_lshl_or_b32 v224, v223, 3, v224
	v_bfe_u32 v223, v222, 3, 1
	v_lshl_or_b32 v224, v223, 4, v224
	v_sub_u32_e32 v224, v224, v222
	v_and_b32_e32 v222, 7, v222
	v_mul_i32_i24_e32 v224, s99, v224
	v_lshlrev_b32_e32 v222, 4, v222
	v_ashrrev_i32_e32 v225, 31, v224
	v_xor_b32_e32 v98, v98, v222
	v_lshl_add_u64 v[100:101], v[100:101], 0, v[224:225]
	v_xor_b32_e32 v100, v100, v222
	v_xor_b32_e32 v102, v102, v222
	v_lshl_add_u64 v[104:105], v[104:105], 0, v[224:225]
	v_xor_b32_e32 v104, v104, v222
	v_xor_b32_e32 v106, v106, v222
	v_lshl_add_u64 v[108:109], v[108:109], 0, v[224:225]
	v_xor_b32_e32 v108, v108, v222
	v_xor_b32_e32 v110, v110, v222
	v_lshl_add_u64 v[112:113], v[112:113], 0, v[224:225]
	v_xor_b32_e32 v112, v112, v222
	s_mov_b64 s[28:29], 0
	s_mov_b32 s5, 0
	v_mov_b32_e32 v75, v74
	v_mov_b32_e32 v76, v74
	v_mov_b32_e32 v77, v74
	v_mov_b32_e32 v62, v74
	v_mov_b32_e32 v63, v74
	v_mov_b32_e32 v64, v74
	v_mov_b32_e32 v65, v74
	v_mov_b32_e32 v66, v74
	v_mov_b32_e32 v67, v74
	v_mov_b32_e32 v68, v74
	v_mov_b32_e32 v69, v74
	v_mov_b32_e32 v58, v74
	v_mov_b32_e32 v59, v74
	v_mov_b32_e32 v60, v74
	v_mov_b32_e32 v61, v74
	v_mov_b32_e32 v70, v74
	v_mov_b32_e32 v71, v74
	v_mov_b32_e32 v72, v74
	v_mov_b32_e32 v73, v74
	v_mov_b32_e32 v54, v74
	v_mov_b32_e32 v55, v74
	v_mov_b32_e32 v56, v74
	v_mov_b32_e32 v57, v74
	v_mov_b32_e32 v78, v74
	v_mov_b32_e32 v79, v74
	v_mov_b32_e32 v80, v74
	v_mov_b32_e32 v81, v74
	v_mov_b32_e32 v50, v74
	v_mov_b32_e32 v51, v74
	v_mov_b32_e32 v52, v74
	v_mov_b32_e32 v53, v74
	v_mov_b32_e32 v82, v74
	v_mov_b32_e32 v83, v74
	v_mov_b32_e32 v84, v74
	v_mov_b32_e32 v85, v74
	v_mov_b32_e32 v46, v74
	v_mov_b32_e32 v47, v74
	v_mov_b32_e32 v48, v74
	v_mov_b32_e32 v49, v74
	v_mov_b32_e32 v86, v74
	v_mov_b32_e32 v87, v74
	v_mov_b32_e32 v88, v74
	v_mov_b32_e32 v89, v74
	v_mov_b32_e32 v42, v74
	v_mov_b32_e32 v43, v74
	v_mov_b32_e32 v44, v74
	v_mov_b32_e32 v45, v74
	v_mov_b32_e32 v90, v74
	v_mov_b32_e32 v91, v74
	v_mov_b32_e32 v92, v74
	v_mov_b32_e32 v93, v74
	v_mov_b32_e32 v38, v74
	v_mov_b32_e32 v39, v74
	v_mov_b32_e32 v40, v74
	v_mov_b32_e32 v41, v74
	v_mov_b32_e32 v94, v74
	v_mov_b32_e32 v95, v74
	v_mov_b32_e32 v96, v74
	v_mov_b32_e32 v97, v74
	v_mov_b32_e32 v34, v74
	v_mov_b32_e32 v35, v74
	v_mov_b32_e32 v36, v74
	v_mov_b32_e32 v37, v74
	s_waitcnt vmcnt(0)
	s_waitcnt lgkmcnt(0)
	s_barrier
.LBB0_237:
	s_setprio 1
	s_add_u32 s98, s28, 0x80
	s_addc_u32 s99, s29, 0
	v_add_u32_e32 v117, v121, v120
	v_add_u32_e32 v119, v121, v122
	v_add_u32_e32 v118, v123, v122
	ds_read_b128 v[124:127], v117 offset:16384
	ds_read_b128 v[128:131], v119
	ds_read_b128 v[140:143], v117 offset:18432
	ds_read_b128 v[160:163], v117 offset:20480
	ds_read_b128 v[164:167], v117 offset:22528
	ds_read_b128 v[132:135], v119 offset:2048
	ds_read_b128 v[152:155], v119 offset:4096
	ds_read_b128 v[156:159], v119 offset:6144
	s_add_u32 m0, s100, 0x8000
	s_waitcnt lgkmcnt(6)
	v_mfma_f32_16x16x32_bf16 v[34:37], v[124:127], v[128:131], v[34:37]
	v_lshl_add_u64 v[194:195], v[98:99], 0, s[98:99]
	global_load_lds_dwordx4 v[194:195], off
	s_waitcnt lgkmcnt(5)
	v_mfma_f32_16x16x32_bf16 v[94:97], v[140:143], v[128:131], v[94:97]
	ds_read_b128 v[198:201], v118
	s_add_u32 m0, s100, 0xc000
	s_waitcnt lgkmcnt(5)
	v_mfma_f32_16x16x32_bf16 v[38:41], v[160:163], v[128:131], v[38:41]
	v_lshl_add_u64 v[196:197], v[100:101], 0, s[98:99]
	global_load_lds_dwordx4 v[196:197], off
	s_add_i32 s5, s5, 2
	s_waitcnt lgkmcnt(4)
	v_mfma_f32_16x16x32_bf16 v[90:93], v[164:167], v[128:131], v[90:93]
	v_add_u32_e32 v130, v123, v120
	ds_read_b128 v[206:209], v118 offset:2048
	s_add_u32 m0, s100, 0x9000
	s_waitcnt lgkmcnt(4)
	v_mfma_f32_16x16x32_bf16 v[42:45], v[124:127], v[132:135], v[42:45]
	v_lshl_add_u64 v[202:203], v[102:103], 0, s[98:99]
	global_load_lds_dwordx4 v[202:203], off
	v_mfma_f32_16x16x32_bf16 v[86:89], v[140:143], v[132:135], v[86:89]
	ds_read_b128 v[214:217], v118 offset:4096
	s_add_u32 m0, s100, 0xd000
	v_mfma_f32_16x16x32_bf16 v[46:49], v[160:163], v[132:135], v[46:49]
	v_lshl_add_u64 v[204:205], v[104:105], 0, s[98:99]
	global_load_lds_dwordx4 v[204:205], off
	v_mfma_f32_16x16x32_bf16 v[82:85], v[164:167], v[132:135], v[82:85]
	ds_read_b128 v[132:135], v118 offset:6144
	s_add_u32 m0, s100, 0xa000
	s_waitcnt lgkmcnt(5)
	v_mfma_f32_16x16x32_bf16 v[50:53], v[124:127], v[152:155], v[50:53]
	v_lshl_add_u64 v[210:211], v[106:107], 0, s[98:99]
	global_load_lds_dwordx4 v[210:211], off
	v_mfma_f32_16x16x32_bf16 v[78:81], v[140:143], v[152:155], v[78:81]
	ds_read_b128 v[226:229], v130 offset:16384
	s_add_u32 m0, s100, 0xe000
	v_mfma_f32_16x16x32_bf16 v[54:57], v[160:163], v[152:155], v[54:57]
	v_lshl_add_u64 v[212:213], v[108:109], 0, s[98:99]
	global_load_lds_dwordx4 v[212:213], off
	v_mfma_f32_16x16x32_bf16 v[70:73], v[164:167], v[152:155], v[70:73]
	ds_read_b128 v[152:155], v130 offset:18432
	s_add_u32 m0, s100, 0xb000
	s_waitcnt lgkmcnt(6)
	v_mfma_f32_16x16x32_bf16 v[58:61], v[124:127], v[156:159], v[58:61]
	v_lshl_add_u64 v[218:219], v[110:111], 0, s[98:99]
	global_load_lds_dwordx4 v[218:219], off
	v_mfma_f32_16x16x32_bf16 v[66:69], v[140:143], v[156:159], v[66:69]
	ds_read_b128 v[140:143], v130 offset:20480
	s_add_u32 m0, s100, 0xf000
	v_mfma_f32_16x16x32_bf16 v[62:65], v[160:163], v[156:159], v[62:65]
	v_lshl_add_u64 v[220:221], v[112:113], 0, s[98:99]
	global_load_lds_dwordx4 v[220:221], off
	v_mfma_f32_16x16x32_bf16 v[74:77], v[164:167], v[156:159], v[74:77]
	ds_read_b128 v[156:159], v130 offset:22528
	s_waitcnt lgkmcnt(3)
	v_mfma_f32_16x16x32_bf16 v[34:37], v[226:229], v[198:201], v[34:37]
	s_waitcnt lgkmcnt(2)
	v_mfma_f32_16x16x32_bf16 v[94:97], v[152:155], v[198:201], v[94:97]
	s_waitcnt lgkmcnt(1)
	v_mfma_f32_16x16x32_bf16 v[38:41], v[140:143], v[198:201], v[38:41]
	s_waitcnt lgkmcnt(0)
	v_mfma_f32_16x16x32_bf16 v[90:93], v[156:159], v[198:201], v[90:93]
	v_mfma_f32_16x16x32_bf16 v[42:45], v[226:229], v[206:209], v[42:45]
	v_mfma_f32_16x16x32_bf16 v[86:89], v[152:155], v[206:209], v[86:89]
	v_mfma_f32_16x16x32_bf16 v[46:49], v[140:143], v[206:209], v[46:49]
	v_mfma_f32_16x16x32_bf16 v[82:85], v[156:159], v[206:209], v[82:85]
	v_mfma_f32_16x16x32_bf16 v[50:53], v[226:229], v[214:217], v[50:53]
	v_mfma_f32_16x16x32_bf16 v[78:81], v[152:155], v[214:217], v[78:81]
	v_mfma_f32_16x16x32_bf16 v[54:57], v[140:143], v[214:217], v[54:57]
	v_mfma_f32_16x16x32_bf16 v[70:73], v[156:159], v[214:217], v[70:73]
	v_mfma_f32_16x16x32_bf16 v[58:61], v[226:229], v[132:135], v[58:61]
	v_mfma_f32_16x16x32_bf16 v[66:69], v[152:155], v[132:135], v[66:69]
	v_mfma_f32_16x16x32_bf16 v[62:65], v[140:143], v[132:135], v[62:65]
	v_mfma_f32_16x16x32_bf16 v[74:77], v[156:159], v[132:135], v[74:77]
	s_waitcnt vmcnt(0)
	s_setprio 0
	s_waitcnt lgkmcnt(0)
	s_barrier
	s_setprio 1
	s_add_u32 s98, s28, 0x100
	s_addc_u32 s99, s29, 0
	ds_read_b128 v[26:29], v117 offset:49152
	ds_read_b128 v[10:13], v119 offset:32768
	ds_read_b128 v[30:33], v117 offset:51200
	ds_read_b128 v[152:155], v117 offset:53248
	ds_read_b128 v[156:159], v117 offset:55296
	ds_read_b128 v[18:21], v119 offset:34816
	ds_read_b128 v[132:135], v119 offset:36864
	ds_read_b128 v[140:143], v119 offset:38912
	s_add_u32 m0, s100, 0x0
	s_waitcnt lgkmcnt(6)
	v_mfma_f32_16x16x32_bf16 v[34:37], v[26:29], v[10:13], v[34:37]
	v_lshl_add_u64 v[194:195], v[98:99], 0, s[98:99]
	global_load_lds_dwordx4 v[194:195], off
	s_waitcnt lgkmcnt(5)
	v_mfma_f32_16x16x32_bf16 v[94:97], v[30:33], v[10:13], v[94:97]
	ds_read_b128 v[164:167], v118 offset:32768
	s_add_u32 m0, s100, 0x4000
	s_waitcnt lgkmcnt(5)
	v_mfma_f32_16x16x32_bf16 v[38:41], v[152:155], v[10:13], v[38:41]
	v_lshl_add_u64 v[196:197], v[100:101], 0, s[98:99]
	global_load_lds_dwordx4 v[196:197], off
	s_waitcnt lgkmcnt(4)
	v_mfma_f32_16x16x32_bf16 v[90:93], v[156:159], v[10:13], v[90:93]
	ds_read_b128 v[198:201], v118 offset:34816
	s_add_u32 m0, s100, 0x1000
	s_waitcnt lgkmcnt(4)
	v_mfma_f32_16x16x32_bf16 v[42:45], v[26:29], v[18:21], v[42:45]
	v_lshl_add_u64 v[202:203], v[102:103], 0, s[98:99]
	global_load_lds_dwordx4 v[202:203], off
	v_mfma_f32_16x16x32_bf16 v[86:89], v[30:33], v[18:21], v[86:89]
	ds_read_b128 v[206:209], v118 offset:36864
	s_add_u32 m0, s100, 0x5000
	v_mfma_f32_16x16x32_bf16 v[46:49], v[152:155], v[18:21], v[46:49]
	v_lshl_add_u64 v[204:205], v[104:105], 0, s[98:99]
	global_load_lds_dwordx4 v[204:205], off
	v_mfma_f32_16x16x32_bf16 v[82:85], v[156:159], v[18:21], v[82:85]
	ds_read_b128 v[214:217], v118 offset:38912
	s_add_u32 m0, s100, 0x2000
	s_waitcnt lgkmcnt(5)
	v_mfma_f32_16x16x32_bf16 v[50:53], v[26:29], v[132:135], v[50:53]
	v_lshl_add_u64 v[210:211], v[106:107], 0, s[98:99]
	global_load_lds_dwordx4 v[210:211], off
	v_mfma_f32_16x16x32_bf16 v[78:81], v[30:33], v[132:135], v[78:81]
	ds_read_b128 v[226:229], v130 offset:49152
	s_add_u32 m0, s100, 0x6000
	v_mfma_f32_16x16x32_bf16 v[54:57], v[152:155], v[132:135], v[54:57]
	v_lshl_add_u64 v[212:213], v[108:109], 0, s[98:99]
	global_load_lds_dwordx4 v[212:213], off
	v_mfma_f32_16x16x32_bf16 v[70:73], v[156:159], v[132:135], v[70:73]
	ds_read_b128 v[132:135], v130 offset:51200
	s_add_u32 m0, s100, 0x3000
	s_waitcnt lgkmcnt(6)
	v_mfma_f32_16x16x32_bf16 v[58:61], v[26:29], v[140:143], v[58:61]
	v_lshl_add_u64 v[218:219], v[110:111], 0, s[98:99]
	global_load_lds_dwordx4 v[218:219], off
	v_mfma_f32_16x16x32_bf16 v[66:69], v[30:33], v[140:143], v[66:69]
	ds_read_b128 v[234:237], v130 offset:53248
	s_add_u32 m0, s100, 0x7000
	v_mfma_f32_16x16x32_bf16 v[62:65], v[152:155], v[140:143], v[62:65]
	v_lshl_add_u64 v[220:221], v[112:113], 0, s[98:99]
	global_load_lds_dwordx4 v[220:221], off
	v_mfma_f32_16x16x32_bf16 v[74:77], v[156:159], v[140:143], v[74:77]
	ds_read_b128 v[140:143], v130 offset:55296
	s_waitcnt lgkmcnt(3)
	v_mfma_f32_16x16x32_bf16 v[34:37], v[226:229], v[164:167], v[34:37]
	s_waitcnt lgkmcnt(2)
	v_mfma_f32_16x16x32_bf16 v[94:97], v[132:135], v[164:167], v[94:97]
	s_waitcnt lgkmcnt(1)
	v_mfma_f32_16x16x32_bf16 v[38:41], v[234:237], v[164:167], v[38:41]
	s_waitcnt lgkmcnt(0)
	v_mfma_f32_16x16x32_bf16 v[90:93], v[140:143], v[164:167], v[90:93]
	v_mfma_f32_16x16x32_bf16 v[42:45], v[226:229], v[198:201], v[42:45]
	v_mfma_f32_16x16x32_bf16 v[86:89], v[132:135], v[198:201], v[86:89]
	v_mfma_f32_16x16x32_bf16 v[46:49], v[234:237], v[198:201], v[46:49]
	v_mfma_f32_16x16x32_bf16 v[82:85], v[140:143], v[198:201], v[82:85]
	v_mfma_f32_16x16x32_bf16 v[50:53], v[226:229], v[206:209], v[50:53]
	v_mfma_f32_16x16x32_bf16 v[78:81], v[132:135], v[206:209], v[78:81]
	v_mfma_f32_16x16x32_bf16 v[54:57], v[234:237], v[206:209], v[54:57]
	v_mfma_f32_16x16x32_bf16 v[70:73], v[140:143], v[206:209], v[70:73]
	v_mfma_f32_16x16x32_bf16 v[58:61], v[226:229], v[214:217], v[58:61]
	v_mfma_f32_16x16x32_bf16 v[66:69], v[132:135], v[214:217], v[66:69]
	v_mfma_f32_16x16x32_bf16 v[62:65], v[234:237], v[214:217], v[62:65]
	v_mfma_f32_16x16x32_bf16 v[74:77], v[140:143], v[214:217], v[74:77]
	s_add_u32 s28, s28, 0x100
	v_cmp_ge_u32_e32 vcc, s5, v116
	s_addc_u32 s29, s29, 0
	s_waitcnt vmcnt(0)
	s_setprio 0
	s_waitcnt lgkmcnt(0)
	s_barrier
	s_cbranch_vccz .LBB0_237
	s_add_u32 s98, s28, 0x80
	s_addc_u32 s99, s29, 0
	v_lshl_add_u64 v[2:3], v[98:99], 0, s[98:99]
	v_lshl_add_u64 v[4:5], v[100:101], 0, s[98:99]
	v_lshl_add_u64 v[6:7], v[102:103], 0, s[98:99]
	v_lshl_add_u64 v[8:9], v[104:105], 0, s[98:99]
	v_lshl_add_u64 v[14:15], v[106:107], 0, s[98:99]
	v_lshl_add_u64 v[16:17], v[108:109], 0, s[98:99]
	v_lshl_add_u64 v[22:23], v[110:111], 0, s[98:99]
	v_lshl_add_u64 v[24:25], v[112:113], 0, s[98:99]
	s_add_i32 s5, s9, 1
	s_cmp_eq_u32 s5, 3
	s_cselect_b32 s11, s8, 0
	s_cselect_b32 s10, 0, s5
	s_add_i32 s11, s11, s4
	s_cmpk_lt_u32 s11, 0x100
	s_cselect_b64 s[50:51], -1, 0
	s_and_b64 s[14:15], s[50:51], exec
	s_cselect_b32 s5, s11, s4
	s_cselect_b32 s4, s10, s9
	s_lshr_b32 s14, s5, 3
	s_and_b32 s14, s14, 0x1fffff8
	s_add_i32 s14, s14, s21
	s_and_b32 s15, s5, 7
	s_or_b32 s14, s14, s15
	s_lshl_b32 s5, s5, 4
	s_lshl_b32 s14, s14, 7
	s_and_b32 s15, s5, 0x380
	s_cmp_lg_u32 s4, 0
	s_cselect_b64 s[48:49], -1, 0
	s_and_b64 vcc, exec, s[48:49]
	s_cbranch_vccz .LBB0_308
	s_movk_i32 s101, 0x400
	v_mov_b32_e32 v0, v169
	s_lshl_b32 s4, s4, 10
	v_mov_b32_e32 v99, v169
	s_or_b32 s4, s4, s15
	v_lshrrev_b32_e32 v98, 3, v0
	v_lshlrev_b32_e32 v0, 3, v0
	s_add_i32 s4, s4, 0x3ffc00
	v_lshrrev_b32_e32 v101, 3, v99
	v_lshlrev_b32_e32 v99, 3, v99
	v_add_u32_e32 v98, s14, v98
	v_and_b32_e32 v0, 56, v0
	v_add_u32_e32 v101, s4, v101
	v_and_b32_e32 v99, 56, v99
	v_lshl_or_b32 v0, v98, 10, v0
	v_lshl_or_b32 v110, v101, 10, v99
	v_add_u32_e32 v104, 0x8000, v0
	v_add_u32_e32 v100, 0x10000, v0
	v_add_u32_e32 v98, 0x18000, v0
	v_add_u32_e32 v108, 0x8000, v110
	v_add_u32_e32 v106, 0x10000, v110
	v_add_u32_e32 v102, 0x18000, v110
	s_mov_b64 s[28:29], s[44:45]
	s_mov_b64 s[34:35], s[0:1]
	s_cbranch_execnz .LBB0_241
.LBB0_240:
	s_movk_i32 s101, 0x200
	v_mov_b32_e32 v0, v169
	v_mov_b32_e32 v99, v169
	s_mov_b64 s[28:29], s[42:43]
	v_lshrrev_b32_e32 v98, 3, v0
	v_lshlrev_b32_e32 v0, 3, v0
	v_lshrrev_b32_e32 v101, 3, v99
	v_lshlrev_b32_e32 v99, 3, v99
	v_add_u32_e32 v98, s14, v98
	v_and_b32_e32 v0, 56, v0
	v_add_u32_e32 v101, s15, v101
	v_and_b32_e32 v99, 56, v99
	v_lshl_or_b32 v0, v98, 9, v0
	v_lshl_or_b32 v110, v101, 9, v99
	v_add_u32_e32 v104, 0x4000, v0
	v_add_u32_e32 v100, 0x8000, v0
	v_add_u32_e32 v98, 0xc000, v0
	v_add_u32_e32 v108, 0x4000, v110
	v_add_u32_e32 v106, 0x8000, v110
	v_add_u32_e32 v102, 0xc000, v110
	s_mov_b64 s[34:35], s[38:39]
.LBB0_241:
	s_setprio 1
	ds_read_b128 v[120:123], v117 offset:16384
	ds_read_b128 v[124:127], v119
	ds_read_b128 v[140:143], v117 offset:18432
	ds_read_b128 v[160:163], v117 offset:20480
	ds_read_b128 v[164:167], v117 offset:22528
	ds_read_b128 v[132:135], v119 offset:2048
	ds_read_b128 v[152:155], v119 offset:4096
	ds_read_b128 v[156:159], v119 offset:6144
	v_lshrrev_b32_e32 v30, 3, v169
	v_and_b32_e32 v31, 3, v30
	v_bfe_u32 v32, v30, 4, 1
	v_lshl_or_b32 v31, v32, 2, v31
	v_bfe_u32 v32, v30, 2, 1
	v_lshl_or_b32 v31, v32, 3, v31
	v_bfe_u32 v32, v30, 3, 1
	v_lshl_or_b32 v31, v32, 4, v31
	v_sub_u32_e32 v31, v31, v30
	v_and_b32_e32 v30, 7, v30
	v_mul_i32_i24_e32 v31, s101, v31
	v_lshlrev_b32_e32 v30, 3, v30
	v_xor_b32_e32 v0, v0, v30
	v_add_u32_e32 v110, v110, v31
	v_xor_b32_e32 v110, v110, v30
	v_xor_b32_e32 v104, v104, v30
	v_add_u32_e32 v108, v108, v31
	v_xor_b32_e32 v108, v108, v30
	v_xor_b32_e32 v100, v100, v30
	v_add_u32_e32 v106, v106, v31
	v_xor_b32_e32 v106, v106, v30
	v_xor_b32_e32 v98, v98, v30
	v_add_u32_e32 v102, v102, v31
	v_xor_b32_e32 v102, v102, v30
	v_mov_b32_e32 v111, v1
	v_mov_b32_e32 v105, v1
	v_mov_b32_e32 v109, v1
	v_mov_b32_e32 v101, v1
	v_mov_b32_e32 v107, v1
	v_mov_b32_e32 v99, v1
	v_mov_b32_e32 v103, v1
	v_lshl_add_u64 v[128:129], v[0:1], 1, s[34:35]
	v_lshl_add_u64 v[136:137], v[110:111], 1, s[28:29]
	v_lshl_add_u64 v[144:145], v[104:105], 1, s[34:35]
	v_lshl_add_u64 v[174:175], v[108:109], 1, s[28:29]
	v_lshl_add_u64 v[176:177], v[100:101], 1, s[34:35]
	v_lshl_add_u64 v[178:179], v[106:107], 1, s[28:29]
	v_lshl_add_u64 v[180:181], v[98:99], 1, s[34:35]
	v_lshl_add_u64 v[186:187], v[102:103], 1, s[28:29]
	s_add_u32 m0, s100, 0x8000
	s_waitcnt lgkmcnt(6)
	v_mfma_f32_16x16x32_bf16 v[194:197], v[120:123], v[124:127], v[34:37]
	global_load_lds_dwordx4 v[2:3], off
	s_waitcnt lgkmcnt(5)
	v_mfma_f32_16x16x32_bf16 v[94:97], v[140:143], v[124:127], v[94:97]
	ds_read_b128 v[198:201], v118
	s_add_u32 m0, s100, 0xc000
	s_waitcnt lgkmcnt(5)
	v_mfma_f32_16x16x32_bf16 v[202:205], v[160:163], v[124:127], v[38:41]
	global_load_lds_dwordx4 v[4:5], off
	s_waitcnt lgkmcnt(4)
	v_mfma_f32_16x16x32_bf16 v[90:93], v[164:167], v[124:127], v[90:93]
	ds_read_b128 v[110:113], v118 offset:2048
	s_add_u32 m0, s100, 0x9000
	s_waitcnt lgkmcnt(4)
	v_mfma_f32_16x16x32_bf16 v[124:127], v[120:123], v[132:135], v[42:45]
	global_load_lds_dwordx4 v[6:7], off
	v_mfma_f32_16x16x32_bf16 v[86:89], v[140:143], v[132:135], v[86:89]
	ds_read_b128 v[206:209], v118 offset:4096
	s_add_u32 m0, s100, 0xd000
	v_mfma_f32_16x16x32_bf16 v[210:213], v[160:163], v[132:135], v[46:49]
	global_load_lds_dwordx4 v[8:9], off
	v_mfma_f32_16x16x32_bf16 v[82:85], v[164:167], v[132:135], v[82:85]
	ds_read_b128 v[132:135], v118 offset:6144
	s_add_u32 m0, s100, 0xa000
	s_waitcnt lgkmcnt(5)
	v_mfma_f32_16x16x32_bf16 v[214:217], v[120:123], v[152:155], v[50:53]
	global_load_lds_dwordx4 v[14:15], off
	v_mfma_f32_16x16x32_bf16 v[78:81], v[140:143], v[152:155], v[78:81]
	ds_read_b128 v[218:221], v130 offset:16384
	s_add_u32 m0, s100, 0xe000
	v_mfma_f32_16x16x32_bf16 v[222:225], v[160:163], v[152:155], v[54:57]
	global_load_lds_dwordx4 v[16:17], off
	v_mfma_f32_16x16x32_bf16 v[70:73], v[164:167], v[152:155], v[70:73]
	ds_read_b128 v[104:107], v130 offset:18432
	s_add_u32 m0, s100, 0xb000
	s_waitcnt lgkmcnt(6)
	v_mfma_f32_16x16x32_bf16 v[120:123], v[120:123], v[156:159], v[58:61]
	global_load_lds_dwordx4 v[22:23], off
	v_mfma_f32_16x16x32_bf16 v[66:69], v[140:143], v[156:159], v[66:69]
	ds_read_b128 v[98:101], v130 offset:20480
	s_add_u32 m0, s100, 0xf000
	v_mfma_f32_16x16x32_bf16 v[140:143], v[160:163], v[156:159], v[62:65]
	global_load_lds_dwordx4 v[24:25], off
	v_mfma_f32_16x16x32_bf16 v[74:77], v[164:167], v[156:159], v[74:77]
	ds_read_b128 v[152:155], v130 offset:22528
	s_waitcnt lgkmcnt(3)
	v_mfma_f32_16x16x32_bf16 v[156:159], v[218:221], v[198:201], v[194:197]
	s_waitcnt lgkmcnt(2)
	v_mfma_f32_16x16x32_bf16 v[94:97], v[104:107], v[198:201], v[94:97]
	s_waitcnt lgkmcnt(1)
	v_mfma_f32_16x16x32_bf16 v[160:163], v[98:101], v[198:201], v[202:205]
	s_waitcnt lgkmcnt(0)
	v_mfma_f32_16x16x32_bf16 v[90:93], v[152:155], v[198:201], v[90:93]
	v_mfma_f32_16x16x32_bf16 v[124:127], v[218:221], v[110:113], v[124:127]
	v_mfma_f32_16x16x32_bf16 v[86:89], v[104:107], v[110:113], v[86:89]
	v_mfma_f32_16x16x32_bf16 v[164:167], v[98:101], v[110:113], v[210:213]
	v_mfma_f32_16x16x32_bf16 v[82:85], v[152:155], v[110:113], v[82:85]
	v_mfma_f32_16x16x32_bf16 v[108:111], v[218:221], v[206:209], v[214:217]
	v_mfma_f32_16x16x32_bf16 v[78:81], v[104:107], v[206:209], v[78:81]
	v_mfma_f32_16x16x32_bf16 v[194:197], v[98:101], v[206:209], v[222:225]
	v_mfma_f32_16x16x32_bf16 v[70:73], v[152:155], v[206:209], v[70:73]
	v_mfma_f32_16x16x32_bf16 v[120:123], v[218:221], v[132:135], v[120:123]
	v_mfma_f32_16x16x32_bf16 v[66:69], v[104:107], v[132:135], v[66:69]
	v_mfma_f32_16x16x32_bf16 v[98:101], v[98:101], v[132:135], v[140:143]
	v_mfma_f32_16x16x32_bf16 v[74:77], v[152:155], v[132:135], v[74:77]
	s_waitcnt vmcnt(0)
	s_setprio 0
	s_waitcnt lgkmcnt(0)
	s_barrier
	s_setprio 1
	ds_read_b128 v[26:29], v117 offset:49152
	ds_read_b128 v[10:13], v119 offset:32768
	ds_read_b128 v[30:33], v117 offset:51200
	ds_read_b128 v[132:135], v117 offset:53248
	ds_read_b128 v[140:143], v117 offset:55296
	ds_read_b128 v[18:21], v119 offset:34816
	ds_read_b128 v[102:105], v119 offset:36864
	ds_read_b128 v[112:115], v119 offset:38912
	s_add_u32 m0, s100, 0x0
	s_waitcnt lgkmcnt(6)
	v_mfma_f32_16x16x32_bf16 v[152:155], v[26:29], v[10:13], v[156:159]
	global_load_lds_dwordx4 v[128:129], off
	s_waitcnt lgkmcnt(5)
	v_mfma_f32_16x16x32_bf16 v[94:97], v[30:33], v[10:13], v[94:97]
	ds_read_b128 v[156:159], v118 offset:32768
	s_add_u32 m0, s100, 0x4000
	s_waitcnt lgkmcnt(5)
	v_mfma_f32_16x16x32_bf16 v[160:163], v[132:135], v[10:13], v[160:163]
	global_load_lds_dwordx4 v[136:137], off
	s_waitcnt lgkmcnt(4)
	v_mfma_f32_16x16x32_bf16 v[90:93], v[140:143], v[10:13], v[90:93]
	ds_read_b128 v[198:201], v118 offset:34816
	s_add_u32 m0, s100, 0x1000
	s_waitcnt lgkmcnt(4)
	v_mfma_f32_16x16x32_bf16 v[202:205], v[26:29], v[18:21], v[124:127]
	global_load_lds_dwordx4 v[144:145], off
	v_mfma_f32_16x16x32_bf16 v[86:89], v[30:33], v[18:21], v[86:89]
	ds_read_b128 v[206:209], v118 offset:36864
	s_add_u32 m0, s100, 0x5000
	v_mfma_f32_16x16x32_bf16 v[164:167], v[132:135], v[18:21], v[164:167]
	global_load_lds_dwordx4 v[174:175], off
	v_mfma_f32_16x16x32_bf16 v[82:85], v[140:143], v[18:21], v[82:85]
	ds_read_b128 v[210:213], v118 offset:38912
	s_add_u32 m0, s100, 0x2000
	s_waitcnt lgkmcnt(5)
	v_mfma_f32_16x16x32_bf16 v[214:217], v[26:29], v[102:105], v[108:111]
	global_load_lds_dwordx4 v[176:177], off
	v_mfma_f32_16x16x32_bf16 v[78:81], v[30:33], v[102:105], v[78:81]
	ds_read_b128 v[218:221], v130 offset:49152
	s_add_u32 m0, s100, 0x6000
	v_mfma_f32_16x16x32_bf16 v[194:197], v[132:135], v[102:105], v[194:197]
	global_load_lds_dwordx4 v[178:179], off
	v_mfma_f32_16x16x32_bf16 v[70:73], v[140:143], v[102:105], v[70:73]
	ds_read_b128 v[222:225], v130 offset:51200
	s_add_u32 m0, s100, 0x3000
	s_waitcnt lgkmcnt(6)
	v_mfma_f32_16x16x32_bf16 v[226:229], v[26:29], v[112:115], v[120:123]
	global_load_lds_dwordx4 v[180:181], off
	v_mfma_f32_16x16x32_bf16 v[66:69], v[30:33], v[112:115], v[66:69]
	ds_read_b128 v[230:233], v130 offset:53248
	s_add_u32 m0, s100, 0x7000
	v_mfma_f32_16x16x32_bf16 v[132:135], v[132:135], v[112:115], v[98:101]
	global_load_lds_dwordx4 v[186:187], off
	v_mfma_f32_16x16x32_bf16 v[140:143], v[140:143], v[112:115], v[74:77]
	s_waitcnt lgkmcnt(2)
	v_mfma_f32_16x16x32_bf16 v[126:129], v[218:221], v[156:159], v[152:155]
	ds_read_b128 v[152:155], v130 offset:55296
	s_waitcnt lgkmcnt(2)
	v_mfma_f32_16x16x32_bf16 v[122:125], v[222:225], v[156:159], v[94:97]
	s_waitcnt lgkmcnt(1)
	v_mfma_f32_16x16x32_bf16 v[118:121], v[230:233], v[156:159], v[160:163]
	s_waitcnt lgkmcnt(0)
	v_mfma_f32_16x16x32_bf16 v[114:117], v[152:155], v[156:159], v[90:93]
	v_mfma_f32_16x16x32_bf16 v[110:113], v[218:221], v[198:201], v[202:205]
	v_mfma_f32_16x16x32_bf16 v[106:109], v[222:225], v[198:201], v[86:89]
	v_mfma_f32_16x16x32_bf16 v[102:105], v[230:233], v[198:201], v[164:167]
	v_mfma_f32_16x16x32_bf16 v[98:101], v[152:155], v[198:201], v[82:85]
	v_mfma_f32_16x16x32_bf16 v[94:97], v[218:221], v[206:209], v[214:217]
	v_mfma_f32_16x16x32_bf16 v[90:93], v[222:225], v[206:209], v[78:81]
	v_mfma_f32_16x16x32_bf16 v[86:89], v[230:233], v[206:209], v[194:197]
	v_mfma_f32_16x16x32_bf16 v[82:85], v[152:155], v[206:209], v[70:73]
	v_mfma_f32_16x16x32_bf16 v[78:81], v[218:221], v[210:213], v[226:229]
	v_mfma_f32_16x16x32_bf16 v[74:77], v[222:225], v[210:213], v[66:69]
	v_mfma_f32_16x16x32_bf16 v[66:69], v[230:233], v[210:213], v[132:135]
	v_mfma_f32_16x16x32_bf16 v[70:73], v[152:155], v[210:213], v[140:143]
	s_setprio 0
	v_add_u32_e32 v130, s25, v146
	v_ashrrev_i32_e32 v131, 31, v130
	v_lshlrev_b64 v[142:143], 10, v[130:131]
	v_lshlrev_b64 v[130:131], 11, v[130:131]
	v_or_b32_e32 v0, s2, v147
	v_lshl_add_u64 v[130:131], s[46:47], 0, v[130:131]
	v_lshl_add_u64 v[140:141], v[0:1], 1, v[130:131]
	s_cmp_lt_i32 s9, 2
	s_mov_b64 s[28:29], -1
	s_barrier
	s_cbranch_scc1 .LBB0_245
	s_cmp_eq_u32 s9, 2
	v_mov_b32_e32 v133, v125
	v_mov_b32_e32 v132, v124
	v_mov_b32_e32 v135, v123
	v_mov_b32_e32 v134, v122
	v_mov_b32_e32 v131, v129
	v_mov_b32_e32 v130, v128
	v_mov_b32_e32 v145, v127
	v_mov_b32_e32 v144, v126
	s_cbranch_scc0 .LBB0_244
	v_lshl_add_u64 v[130:131], v[142:143], 1, s[40:41]
	v_lshl_add_u64 v[130:131], v[0:1], 1, v[130:131]
	global_load_dwordx4 v[130:133], v[130:131], off
	v_mul_f32_e32 v138, 0xbfb8aa3b, v126
	global_load_dwordx4 v[134:137], v[140:141], off
	v_exp_f32_e32 v138, v138
	s_waitcnt vmcnt(1)
	v_lshlrev_b32_e32 v154, 16, v130
	v_add_f32_e32 v138, 1.0, v138
	v_rcp_f32_e32 v144, v138
	v_mul_f32_e32 v138, 0xbfb8aa3b, v127
	v_exp_f32_e32 v138, v138
	v_and_b32_e32 v155, 0xffff0000, v130
	v_mul_f32_e32 v130, 0xbfb8aa3b, v128
	v_exp_f32_e32 v130, v130
	v_add_f32_e32 v138, 1.0, v138
	v_rcp_f32_e32 v145, v138
	s_waitcnt vmcnt(0)
	v_lshlrev_b32_e32 v152, 16, v134
	v_and_b32_e32 v153, 0xffff0000, v134
	v_add_f32_e32 v130, 1.0, v130
	v_pk_fma_f32 v[144:145], v[144:145], v[154:155], v[152:153]
	v_rcp_f32_e32 v152, v130
	v_mul_f32_e32 v130, 0xbfb8aa3b, v129
	v_exp_f32_e32 v130, v130
	v_lshlrev_b32_e32 v134, 16, v135
	v_and_b32_e32 v135, 0xffff0000, v135
	v_lshlrev_b32_e32 v154, 16, v132
	v_add_f32_e32 v130, 1.0, v130
	v_rcp_f32_e32 v153, v130
	v_lshlrev_b32_e32 v130, 16, v131
	v_and_b32_e32 v131, 0xffff0000, v131
	v_and_b32_e32 v155, 0xffff0000, v132
	v_pk_fma_f32 v[130:131], v[152:153], v[130:131], v[134:135]
	v_mul_f32_e32 v134, 0xbfb8aa3b, v122
	v_mul_f32_e32 v135, 0xbfb8aa3b, v123
	v_exp_f32_e32 v134, v134
	v_exp_f32_e32 v135, v135
	v_mul_f32_e32 v132, 0xbfb8aa3b, v124
	v_exp_f32_e32 v132, v132
	v_add_f32_e32 v134, 1.0, v134
	v_add_f32_e32 v135, 1.0, v135
	v_rcp_f32_e32 v134, v134
	v_rcp_f32_e32 v135, v135
	v_lshlrev_b32_e32 v152, 16, v136
	v_and_b32_e32 v153, 0xffff0000, v136
	v_add_f32_e32 v132, 1.0, v132
	v_pk_fma_f32 v[134:135], v[134:135], v[154:155], v[152:153]
	v_rcp_f32_e32 v152, v132
	v_mul_f32_e32 v132, 0xbfb8aa3b, v125
	v_exp_f32_e32 v132, v132
	v_lshlrev_b32_e32 v136, 16, v137
	v_and_b32_e32 v137, 0xffff0000, v137
	v_add_f32_e32 v132, 1.0, v132
	v_rcp_f32_e32 v153, v132
	v_lshlrev_b32_e32 v132, 16, v133
	v_and_b32_e32 v133, 0xffff0000, v133
	v_pk_fma_f32 v[132:133], v[152:153], v[132:133], v[136:137]

.LBB0_475:
	s_setprio 1
	s_add_u32 s98, s28, 0x80
	s_addc_u32 s99, s29, 0
	v_add_u32_e32 v120, v117, v116
	v_add_u32_e32 v122, v117, v118
	v_add_u32_e32 v121, v119, v118
	ds_read_b128 v[124:127], v120 offset:16384
	ds_read_b128 v[128:131], v122
	ds_read_b128 v[144:147], v120 offset:18432
	ds_read_b128 v[156:159], v120 offset:20480
	ds_read_b128 v[160:163], v120 offset:22528
	ds_read_b128 v[132:135], v122 offset:2048
	ds_read_b128 v[148:151], v122 offset:4096
	ds_read_b128 v[152:155], v122 offset:6144
	s_add_u32 m0, s100, 0x8000
	s_waitcnt lgkmcnt(6)
	v_mfma_f32_16x16x32_bf16 v[34:37], v[124:127], v[128:131], v[34:37]
	global_load_lds_dwordx4 v164, s[98:99]
	s_waitcnt lgkmcnt(5)
	v_mfma_f32_16x16x32_bf16 v[94:97], v[144:147], v[128:131], v[94:97]
	ds_read_b128 v[194:197], v121
	s_add_u32 m0, s100, 0xc000
	s_waitcnt lgkmcnt(5)
	v_mfma_f32_16x16x32_bf16 v[38:41], v[156:159], v[128:131], v[38:41]
	global_load_lds_dwordx4 v165, s[98:99]
	s_waitcnt lgkmcnt(4)
	v_mfma_f32_16x16x32_bf16 v[90:93], v[160:163], v[128:131], v[90:93]
	v_add_u32_e32 v130, v119, v116
	ds_read_b128 v[202:205], v121 offset:2048
	s_add_u32 m0, s100, 0x9000
	s_waitcnt lgkmcnt(4)
	v_mfma_f32_16x16x32_bf16 v[42:45], v[124:127], v[132:135], v[42:45]
	global_load_lds_dwordx4 v166, s[98:99]
	v_mfma_f32_16x16x32_bf16 v[86:89], v[144:147], v[132:135], v[86:89]
	ds_read_b128 v[210:213], v121 offset:4096
	s_add_u32 m0, s100, 0xd000
	v_mfma_f32_16x16x32_bf16 v[46:49], v[156:159], v[132:135], v[46:49]
	global_load_lds_dwordx4 v167, s[98:99]
	v_mfma_f32_16x16x32_bf16 v[82:85], v[160:163], v[132:135], v[82:85]
	ds_read_b128 v[132:135], v121 offset:6144
	s_add_u32 m0, s100, 0xa000
	s_waitcnt lgkmcnt(5)
	v_mfma_f32_16x16x32_bf16 v[50:53], v[124:127], v[148:151], v[50:53]
	global_load_lds_dwordx4 v198, s[98:99]
	v_mfma_f32_16x16x32_bf16 v[78:81], v[144:147], v[148:151], v[78:81]
	ds_read_b128 v[222:225], v130 offset:16384
	s_add_u32 m0, s100, 0xe000
	v_mfma_f32_16x16x32_bf16 v[54:57], v[156:159], v[148:151], v[54:57]
	global_load_lds_dwordx4 v199, s[98:99]
	v_mfma_f32_16x16x32_bf16 v[70:73], v[160:163], v[148:151], v[70:73]
	ds_read_b128 v[148:151], v130 offset:18432
	s_add_u32 m0, s100, 0xb000
	s_waitcnt lgkmcnt(6)
	v_mfma_f32_16x16x32_bf16 v[58:61], v[124:127], v[152:155], v[58:61]
	global_load_lds_dwordx4 v200, s[98:99]
	v_mfma_f32_16x16x32_bf16 v[66:69], v[144:147], v[152:155], v[66:69]
	ds_read_b128 v[144:147], v130 offset:20480
	s_add_u32 m0, s100, 0xf000
	v_mfma_f32_16x16x32_bf16 v[62:65], v[156:159], v[152:155], v[62:65]
	global_load_lds_dwordx4 v201, s[98:99]
	v_mfma_f32_16x16x32_bf16 v[74:77], v[160:163], v[152:155], v[74:77]
	ds_read_b128 v[152:155], v130 offset:22528
	s_waitcnt lgkmcnt(3)
	v_mfma_f32_16x16x32_bf16 v[34:37], v[222:225], v[194:197], v[34:37]
	s_waitcnt lgkmcnt(2)
	v_mfma_f32_16x16x32_bf16 v[94:97], v[148:151], v[194:197], v[94:97]
	s_waitcnt lgkmcnt(1)
	v_mfma_f32_16x16x32_bf16 v[38:41], v[144:147], v[194:197], v[38:41]
	s_waitcnt lgkmcnt(0)
	v_mfma_f32_16x16x32_bf16 v[90:93], v[152:155], v[194:197], v[90:93]
	v_mfma_f32_16x16x32_bf16 v[42:45], v[222:225], v[202:205], v[42:45]
	v_mfma_f32_16x16x32_bf16 v[86:89], v[148:151], v[202:205], v[86:89]
	v_mfma_f32_16x16x32_bf16 v[46:49], v[144:147], v[202:205], v[46:49]
	v_mfma_f32_16x16x32_bf16 v[82:85], v[152:155], v[202:205], v[82:85]
	v_mfma_f32_16x16x32_bf16 v[50:53], v[222:225], v[210:213], v[50:53]
	v_mfma_f32_16x16x32_bf16 v[78:81], v[148:151], v[210:213], v[78:81]
	v_mfma_f32_16x16x32_bf16 v[54:57], v[144:147], v[210:213], v[54:57]
	v_mfma_f32_16x16x32_bf16 v[70:73], v[152:155], v[210:213], v[70:73]
	v_mfma_f32_16x16x32_bf16 v[58:61], v[222:225], v[132:135], v[58:61]
	v_mfma_f32_16x16x32_bf16 v[66:69], v[148:151], v[132:135], v[66:69]
	v_mfma_f32_16x16x32_bf16 v[62:65], v[144:147], v[132:135], v[62:65]
	v_mfma_f32_16x16x32_bf16 v[74:77], v[152:155], v[132:135], v[74:77]
	s_waitcnt vmcnt(0)
	s_setprio 0
	s_waitcnt lgkmcnt(0)
	s_barrier
	s_setprio 1
	s_add_u32 s98, s98, 0x80
	s_addc_u32 s99, s99, 0
	ds_read_b128 v[26:29], v120 offset:49152
	ds_read_b128 v[10:13], v122 offset:32768
	ds_read_b128 v[30:33], v120 offset:51200
	ds_read_b128 v[148:151], v120 offset:53248
	ds_read_b128 v[152:155], v120 offset:55296
	ds_read_b128 v[18:21], v122 offset:34816
	ds_read_b128 v[132:135], v122 offset:36864
	ds_read_b128 v[144:147], v122 offset:38912
	s_add_u32 m0, s100, 0x0
	s_waitcnt lgkmcnt(6)
	v_mfma_f32_16x16x32_bf16 v[34:37], v[26:29], v[10:13], v[34:37]
	global_load_lds_dwordx4 v164, s[98:99]
	s_waitcnt lgkmcnt(5)
	v_mfma_f32_16x16x32_bf16 v[94:97], v[30:33], v[10:13], v[94:97]
	ds_read_b128 v[160:163], v121 offset:32768
	s_add_u32 m0, s100, 0x4000
	s_waitcnt lgkmcnt(5)
	v_mfma_f32_16x16x32_bf16 v[38:41], v[148:151], v[10:13], v[38:41]
	global_load_lds_dwordx4 v165, s[98:99]
	s_waitcnt lgkmcnt(4)
	v_mfma_f32_16x16x32_bf16 v[90:93], v[152:155], v[10:13], v[90:93]
	ds_read_b128 v[194:197], v121 offset:34816
	s_add_u32 m0, s100, 0x1000
	s_waitcnt lgkmcnt(4)
	v_mfma_f32_16x16x32_bf16 v[42:45], v[26:29], v[18:21], v[42:45]
	global_load_lds_dwordx4 v166, s[98:99]
	v_mfma_f32_16x16x32_bf16 v[86:89], v[30:33], v[18:21], v[86:89]
	ds_read_b128 v[202:205], v121 offset:36864
	s_add_u32 m0, s100, 0x5000
	v_mfma_f32_16x16x32_bf16 v[46:49], v[148:151], v[18:21], v[46:49]
	global_load_lds_dwordx4 v167, s[98:99]
	v_mfma_f32_16x16x32_bf16 v[82:85], v[152:155], v[18:21], v[82:85]
	ds_read_b128 v[210:213], v121 offset:38912
	s_add_u32 m0, s100, 0x2000
	s_waitcnt lgkmcnt(5)
	v_mfma_f32_16x16x32_bf16 v[50:53], v[26:29], v[132:135], v[50:53]
	global_load_lds_dwordx4 v198, s[98:99]
	v_mfma_f32_16x16x32_bf16 v[78:81], v[30:33], v[132:135], v[78:81]
	ds_read_b128 v[222:225], v130 offset:49152
	s_add_u32 m0, s100, 0x6000
	v_mfma_f32_16x16x32_bf16 v[54:57], v[148:151], v[132:135], v[54:57]
	global_load_lds_dwordx4 v199, s[98:99]
	v_mfma_f32_16x16x32_bf16 v[70:73], v[152:155], v[132:135], v[70:73]
	ds_read_b128 v[132:135], v130 offset:51200
	s_add_u32 m0, s100, 0x3000
	s_waitcnt lgkmcnt(6)
	v_mfma_f32_16x16x32_bf16 v[58:61], v[26:29], v[144:147], v[58:61]
	global_load_lds_dwordx4 v200, s[98:99]
	v_mfma_f32_16x16x32_bf16 v[66:69], v[30:33], v[144:147], v[66:69]
	ds_read_b128 v[230:233], v130 offset:53248
	s_add_u32 m0, s100, 0x7000
	v_mfma_f32_16x16x32_bf16 v[62:65], v[148:151], v[144:147], v[62:65]
	global_load_lds_dwordx4 v201, s[98:99]
	v_mfma_f32_16x16x32_bf16 v[74:77], v[152:155], v[144:147], v[74:77]
	ds_read_b128 v[144:147], v130 offset:55296
	s_waitcnt lgkmcnt(3)
	v_mfma_f32_16x16x32_bf16 v[34:37], v[222:225], v[160:163], v[34:37]
	s_waitcnt lgkmcnt(2)
	v_mfma_f32_16x16x32_bf16 v[94:97], v[132:135], v[160:163], v[94:97]
	s_waitcnt lgkmcnt(1)
	v_mfma_f32_16x16x32_bf16 v[38:41], v[230:233], v[160:163], v[38:41]
	s_waitcnt lgkmcnt(0)
	v_mfma_f32_16x16x32_bf16 v[90:93], v[144:147], v[160:163], v[90:93]
	v_mfma_f32_16x16x32_bf16 v[42:45], v[222:225], v[194:197], v[42:45]
	v_mfma_f32_16x16x32_bf16 v[86:89], v[132:135], v[194:197], v[86:89]
	v_mfma_f32_16x16x32_bf16 v[46:49], v[230:233], v[194:197], v[46:49]
	v_mfma_f32_16x16x32_bf16 v[82:85], v[144:147], v[194:197], v[82:85]
	v_mfma_f32_16x16x32_bf16 v[50:53], v[222:225], v[202:205], v[50:53]
	v_mfma_f32_16x16x32_bf16 v[78:81], v[132:135], v[202:205], v[78:81]
	v_mfma_f32_16x16x32_bf16 v[54:57], v[230:233], v[202:205], v[54:57]
	v_mfma_f32_16x16x32_bf16 v[70:73], v[144:147], v[202:205], v[70:73]
	v_mfma_f32_16x16x32_bf16 v[58:61], v[222:225], v[210:213], v[58:61]
	v_mfma_f32_16x16x32_bf16 v[66:69], v[132:135], v[210:213], v[66:69]
	v_mfma_f32_16x16x32_bf16 v[62:65], v[230:233], v[210:213], v[62:65]
	v_mfma_f32_16x16x32_bf16 v[74:77], v[144:147], v[210:213], v[74:77]
	s_waitcnt vmcnt(0)
	s_setprio 0
	s_add_i32 s8, s8, 2
	s_add_u32 s28, s28, 0x100
	s_addc_u32 s29, s29, 0
	s_cmp_lt_u32 s8, 12
	s_waitcnt lgkmcnt(0)
	s_barrier
	s_cbranch_scc1 .LBB0_475
	v_mov_b32_e32 v2, v164
	v_mov_b32_e32 v3, v165
	v_mov_b32_e32 v4, v166
	v_mov_b32_e32 v5, v167
	v_mov_b32_e32 v6, v198
	v_mov_b32_e32 v7, v199
	v_mov_b32_e32 v8, v200
	v_mov_b32_e32 v9, v201
	s_add_u32 s98, s28, 0x80
	s_addc_u32 s99, s29, 0
	s_add_i32 s8, s11, s2
	s_cmpk_lt_u32 s8, 0x420
	s_cselect_b64 s[56:57], -1, 0
	s_and_b64 s[14:15], s[56:57], exec
	s_cselect_b32 s10, s8, s11
	s_mul_hi_u32 s11, s10, 0x3e0f83e1
	s_lshr_b32 s11, s11, 6
	s_mul_i32 s14, s11, 0x108
	v_mov_b32_e32 v0, v169
	s_sub_i32 s10, s10, s14
	s_lshl_b32 s11, s11, 3
	s_add_i32 s11, s11, s21
	s_and_b32 s14, s10, 7
	v_lshlrev_b32_e32 v98, 3, v0
	v_lshlrev_b32_e32 v0, 7, v0
	s_or_b32 s11, s11, s14
	v_and_b32_e32 v0, 0xfffffc00, v0
	v_lshl_add_u32 v0, s11, 17, v0
	v_and_or_b32 v0, v98, 56, v0
	v_mov_b32_e32 v98, v169
	s_lshl_b32 s10, s10, 4
	s_and_b32 s10, s10, 0x1f80
	v_lshrrev_b32_e32 v99, 3, v98
	v_lshlrev_b32_e32 v98, 3, v98
	v_add_u32_e32 v99, s10, v99
	v_and_b32_e32 v98, 56, v98
	v_add_u32_e32 v128, 0x8000, v0
	v_add_u32_e32 v136, 0x10000, v0
	v_lshl_or_b32 v160, v99, 10, v98
	v_add_u32_e32 v210, 0x18000, v0
	v_add_u32_e32 v198, 0x8000, v160
	v_add_u32_e32 v212, 0x10000, v160
	v_add_u32_e32 v214, 0x18000, v160
	s_setprio 1
	ds_read_b128 v[98:101], v120 offset:16384
	ds_read_b128 v[102:105], v122
	ds_read_b128 v[110:113], v120 offset:18432
	ds_read_b128 v[132:135], v120 offset:20480
	ds_read_b128 v[144:147], v120 offset:22528
	ds_read_b128 v[106:109], v122 offset:2048
	ds_read_b128 v[116:119], v122 offset:4096
	ds_read_b128 v[124:127], v122 offset:6144
	v_lshrrev_b32_e32 v14, 3, v169
	v_and_b32_e32 v15, 3, v14
	v_bfe_u32 v16, v14, 4, 1
	v_lshl_or_b32 v15, v16, 2, v15
	v_bfe_u32 v16, v14, 2, 1
	v_lshl_or_b32 v15, v16, 3, v15
	v_bfe_u32 v16, v14, 3, 1
	v_lshl_or_b32 v15, v16, 4, v15
	v_sub_u32_e32 v15, v15, v14
	v_mul_i32_i24_e32 v15, 0x400, v15
	v_and_b32_e32 v14, 7, v14
	v_lshlrev_b32_e32 v14, 3, v14
	v_xor_b32_e32 v0, v0, v14
	v_add_u32_e32 v160, v160, v15
	v_xor_b32_e32 v160, v160, v14
	v_xor_b32_e32 v128, v128, v14
	v_add_u32_e32 v198, v198, v15
	v_xor_b32_e32 v198, v198, v14
	v_xor_b32_e32 v136, v136, v14
	v_add_u32_e32 v212, v212, v15
	v_xor_b32_e32 v212, v212, v14
	v_xor_b32_e32 v210, v210, v14
	v_add_u32_e32 v214, v214, v15
	v_xor_b32_e32 v214, v214, v14
	v_mov_b32_e32 v161, v1
	v_mov_b32_e32 v129, v1
	v_mov_b32_e32 v199, v1
	v_mov_b32_e32 v137, v1
	v_mov_b32_e32 v213, v1
	v_mov_b32_e32 v211, v1
	v_mov_b32_e32 v215, v1
	v_lshl_add_u64 v[216:217], v[0:1], 1, s[48:49]
	v_lshl_add_u64 v[218:219], v[160:161], 1, s[50:51]
	v_lshl_add_u64 v[220:221], v[128:129], 1, s[48:49]
	v_lshl_add_u64 v[222:223], v[198:199], 1, s[50:51]
	v_lshl_add_u64 v[136:137], v[136:137], 1, s[48:49]
	v_lshl_add_u64 v[212:213], v[212:213], 1, s[50:51]
	v_lshl_add_u64 v[224:225], v[210:211], 1, s[48:49]
	v_lshl_add_u64 v[226:227], v[214:215], 1, s[50:51]
	s_add_u32 m0, s100, 0x8000
	s_waitcnt lgkmcnt(6)
	v_mfma_f32_16x16x32_bf16 v[148:151], v[98:101], v[102:105], v[34:37]
	global_load_lds_dwordx4 v2, s[98:99]
	s_waitcnt lgkmcnt(5)
	v_mfma_f32_16x16x32_bf16 v[94:97], v[110:113], v[102:105], v[94:97]
	ds_read_b128 v[152:155], v121
	s_add_u32 m0, s100, 0xc000
	s_waitcnt lgkmcnt(5)
	v_mfma_f32_16x16x32_bf16 v[156:159], v[132:135], v[102:105], v[38:41]
	global_load_lds_dwordx4 v3, s[98:99]
	s_waitcnt lgkmcnt(4)
	v_mfma_f32_16x16x32_bf16 v[90:93], v[144:147], v[102:105], v[90:93]
	ds_read_b128 v[102:105], v121 offset:2048
	s_add_u32 m0, s100, 0x9000
	s_waitcnt lgkmcnt(4)
	v_mfma_f32_16x16x32_bf16 v[160:163], v[98:101], v[106:109], v[42:45]
	global_load_lds_dwordx4 v4, s[98:99]
	v_mfma_f32_16x16x32_bf16 v[86:89], v[110:113], v[106:109], v[86:89]
	ds_read_b128 v[164:167], v121 offset:4096
	s_add_u32 m0, s100, 0xd000
	v_mfma_f32_16x16x32_bf16 v[194:197], v[132:135], v[106:109], v[46:49]
	global_load_lds_dwordx4 v5, s[98:99]
	v_mfma_f32_16x16x32_bf16 v[82:85], v[144:147], v[106:109], v[82:85]
	ds_read_b128 v[106:109], v121 offset:6144
	s_add_u32 m0, s100, 0xa000
	s_waitcnt lgkmcnt(5)
	v_mfma_f32_16x16x32_bf16 v[198:201], v[98:101], v[116:119], v[50:53]
	global_load_lds_dwordx4 v6, s[98:99]
	v_mfma_f32_16x16x32_bf16 v[78:81], v[110:113], v[116:119], v[78:81]
	ds_read_b128 v[202:205], v130 offset:16384
	s_add_u32 m0, s100, 0xe000
	v_mfma_f32_16x16x32_bf16 v[206:209], v[132:135], v[116:119], v[54:57]
	global_load_lds_dwordx4 v7, s[98:99]
	v_mfma_f32_16x16x32_bf16 v[70:73], v[144:147], v[116:119], v[70:73]
	ds_read_b128 v[116:119], v130 offset:18432
	s_add_u32 m0, s100, 0xb000
	s_waitcnt lgkmcnt(6)
	v_mfma_f32_16x16x32_bf16 v[98:101], v[98:101], v[124:127], v[58:61]
	global_load_lds_dwordx4 v8, s[98:99]
	v_mfma_f32_16x16x32_bf16 v[66:69], v[110:113], v[124:127], v[66:69]
	ds_read_b128 v[110:113], v130 offset:20480
	s_add_u32 m0, s100, 0xf000
	v_mfma_f32_16x16x32_bf16 v[132:135], v[132:135], v[124:127], v[62:65]
	global_load_lds_dwordx4 v9, s[98:99]
	v_mfma_f32_16x16x32_bf16 v[74:77], v[144:147], v[124:127], v[74:77]
	ds_read_b128 v[124:127], v130 offset:22528
	s_waitcnt lgkmcnt(3)
	v_mfma_f32_16x16x32_bf16 v[144:147], v[202:205], v[152:155], v[148:151]
	s_waitcnt lgkmcnt(2)
	v_mfma_f32_16x16x32_bf16 v[94:97], v[116:119], v[152:155], v[94:97]
	s_waitcnt lgkmcnt(1)
	v_mfma_f32_16x16x32_bf16 v[148:151], v[110:113], v[152:155], v[156:159]
	s_waitcnt lgkmcnt(0)
	v_mfma_f32_16x16x32_bf16 v[90:93], v[124:127], v[152:155], v[90:93]
	v_mfma_f32_16x16x32_bf16 v[152:155], v[202:205], v[102:105], v[160:163]
	v_mfma_f32_16x16x32_bf16 v[86:89], v[116:119], v[102:105], v[86:89]
	v_mfma_f32_16x16x32_bf16 v[156:159], v[110:113], v[102:105], v[194:197]
	v_mfma_f32_16x16x32_bf16 v[82:85], v[124:127], v[102:105], v[82:85]
	v_mfma_f32_16x16x32_bf16 v[102:105], v[202:205], v[164:167], v[198:201]
	v_mfma_f32_16x16x32_bf16 v[78:81], v[116:119], v[164:167], v[78:81]
	v_mfma_f32_16x16x32_bf16 v[160:163], v[110:113], v[164:167], v[206:209]
	v_mfma_f32_16x16x32_bf16 v[70:73], v[124:127], v[164:167], v[70:73]
	v_mfma_f32_16x16x32_bf16 v[98:101], v[202:205], v[106:109], v[98:101]
	v_mfma_f32_16x16x32_bf16 v[66:69], v[116:119], v[106:109], v[66:69]
	v_mfma_f32_16x16x32_bf16 v[110:113], v[110:113], v[106:109], v[132:135]
	v_mfma_f32_16x16x32_bf16 v[74:77], v[124:127], v[106:109], v[74:77]
	s_waitcnt vmcnt(0)
	s_setprio 0
	s_waitcnt lgkmcnt(0)
	s_barrier
	s_setprio 1
	ds_read_b128 v[26:29], v120 offset:49152
	ds_read_b128 v[10:13], v122 offset:32768
	ds_read_b128 v[18:21], v122 offset:34816
	ds_read_b128 v[30:33], v120 offset:51200
	ds_read_b128 v[106:109], v122 offset:36864
	ds_read_b128 v[114:117], v122 offset:38912
	ds_read_b128 v[122:125], v120 offset:53248
	ds_read_b128 v[126:129], v120 offset:55296
	s_add_u32 m0, s100, 0x0
	s_waitcnt lgkmcnt(6)
	v_mfma_f32_16x16x32_bf16 v[132:135], v[26:29], v[10:13], v[144:147]
	global_load_lds_dwordx4 v[216:217], off
	s_waitcnt lgkmcnt(4)
	v_mfma_f32_16x16x32_bf16 v[94:97], v[30:33], v[10:13], v[94:97]
	ds_read_b128 v[144:147], v121 offset:32768
	s_add_u32 m0, s100, 0x4000
	s_waitcnt lgkmcnt(2)
	v_mfma_f32_16x16x32_bf16 v[148:151], v[122:125], v[10:13], v[148:151]
	global_load_lds_dwordx4 v[218:219], off
	s_waitcnt lgkmcnt(1)
	v_mfma_f32_16x16x32_bf16 v[90:93], v[126:129], v[10:13], v[90:93]
	ds_read_b128 v[164:167], v121 offset:34816
	s_add_u32 m0, s100, 0x1000
	v_mfma_f32_16x16x32_bf16 v[152:155], v[26:29], v[18:21], v[152:155]
	global_load_lds_dwordx4 v[220:221], off
	v_mfma_f32_16x16x32_bf16 v[86:89], v[30:33], v[18:21], v[86:89]
	ds_read_b128 v[194:197], v121 offset:36864
	s_add_u32 m0, s100, 0x5000
	v_mfma_f32_16x16x32_bf16 v[156:159], v[122:125], v[18:21], v[156:159]
	global_load_lds_dwordx4 v[222:223], off
	v_mfma_f32_16x16x32_bf16 v[82:85], v[126:129], v[18:21], v[82:85]
	ds_read_b128 v[198:201], v121 offset:38912
	s_add_u32 m0, s100, 0x2000
	v_mfma_f32_16x16x32_bf16 v[202:205], v[26:29], v[106:109], v[102:105]
	global_load_lds_dwordx4 v[136:137], off
	v_mfma_f32_16x16x32_bf16 v[78:81], v[30:33], v[106:109], v[78:81]
	ds_read_b128 v[206:209], v130 offset:49152
	s_add_u32 m0, s100, 0x6000
	v_mfma_f32_16x16x32_bf16 v[160:163], v[122:125], v[106:109], v[160:163]
	global_load_lds_dwordx4 v[212:213], off
	v_mfma_f32_16x16x32_bf16 v[70:73], v[126:129], v[106:109], v[70:73]
	ds_read_b128 v[210:213], v130 offset:51200
	s_add_u32 m0, s100, 0x3000
	v_mfma_f32_16x16x32_bf16 v[214:217], v[26:29], v[114:117], v[98:101]
	global_load_lds_dwordx4 v[224:225], off
	v_mfma_f32_16x16x32_bf16 v[66:69], v[30:33], v[114:117], v[66:69]
	ds_read_b128 v[218:221], v130 offset:53248
	s_add_u32 m0, s100, 0x7000
	v_mfma_f32_16x16x32_bf16 v[222:225], v[122:125], v[114:117], v[110:113]
	global_load_lds_dwordx4 v[226:227], off
	v_mfma_f32_16x16x32_bf16 v[226:229], v[126:129], v[114:117], v[74:77]
	s_waitcnt lgkmcnt(2)
	v_mfma_f32_16x16x32_bf16 v[126:129], v[206:209], v[144:147], v[132:135]
	ds_read_b128 v[130:133], v130 offset:55296
	s_waitcnt lgkmcnt(2)
	v_mfma_f32_16x16x32_bf16 v[122:125], v[210:213], v[144:147], v[94:97]
	s_waitcnt lgkmcnt(1)
	v_mfma_f32_16x16x32_bf16 v[118:121], v[218:221], v[144:147], v[148:151]
	s_waitcnt lgkmcnt(0)
	v_mfma_f32_16x16x32_bf16 v[114:117], v[130:133], v[144:147], v[90:93]
	v_mfma_f32_16x16x32_bf16 v[110:113], v[206:209], v[164:167], v[152:155]
	v_mfma_f32_16x16x32_bf16 v[106:109], v[210:213], v[164:167], v[86:89]
	v_mfma_f32_16x16x32_bf16 v[102:105], v[218:221], v[164:167], v[156:159]
	v_mfma_f32_16x16x32_bf16 v[98:101], v[130:133], v[164:167], v[82:85]
	v_mfma_f32_16x16x32_bf16 v[94:97], v[206:209], v[194:197], v[202:205]
	v_mfma_f32_16x16x32_bf16 v[90:93], v[210:213], v[194:197], v[78:81]
	v_mfma_f32_16x16x32_bf16 v[86:89], v[218:221], v[194:197], v[160:163]
	v_mfma_f32_16x16x32_bf16 v[82:85], v[130:133], v[194:197], v[70:73]
	v_mfma_f32_16x16x32_bf16 v[74:77], v[206:209], v[198:201], v[214:217]
	v_mfma_f32_16x16x32_bf16 v[70:73], v[210:213], v[198:201], v[66:69]
	v_mfma_f32_16x16x32_bf16 v[66:69], v[218:221], v[198:201], v[222:225]
	v_mfma_f32_16x16x32_bf16 v[78:81], v[130:133], v[198:201], v[226:229]
	s_setprio 0
	s_cmpk_gt_u32 s16, 0x9ff
	s_cselect_b64 s[42:43], -1, 0
	s_and_b32 s17, s16, 0x1f00
	s_cmpk_eq_i32 s17, 0xe00
	s_cselect_b64 s[40:41], -1, 0
	s_cmpk_gt_u32 s16, 0x5ff
	s_cselect_b64 s[46:47], -1, 0
	s_cmpk_gt_u32 s16, 0xbff
	s_cselect_b64 s[62:63], -1, 0
	s_cmpk_lt_u32 s16, 0xd00
	s_cselect_b64 s[14:15], -1, 0
	s_and_b64 s[26:27], s[14:15], exec
	s_movk_i32 s21, 0xf300
	s_cselect_b32 s28, 0xfffff400, s21
	s_nor_b64 s[60:61], s[14:15], s[40:41]
	s_cmpk_gt_u32 s16, 0xfff
	s_cselect_b64 s[58:59], -1, 0
	s_cmpk_lt_u32 s16, 0xe00
	v_add_u32_e32 v0, s9, v141
	s_cselect_b64 s[14:15], -1, 0
	v_or_b32_e32 v136, v0, v140
	s_movk_i32 s21, 0xc0
	s_and_b64 s[14:15], s[14:15], exec
	v_mad_i64_i32 v[134:135], s[26:27], v136, s21, 0
	s_movk_i32 s21, 0x1fcf
	s_movk_i32 s14, 0xf100
	v_bitop3_b32 v144, v0, s21, v140 bitop3:0xc8
	v_ashrrev_i32_e32 v0, 5, v0
	s_cselect_b32 s15, 0xfffff300, s14
	s_mov_b32 s14, 0x18991000
	v_ashrrev_i32_e32 v137, 31, v136
	v_and_b32_e32 v0, 0xffffff00, v0
	s_cselect_b32 s14, s14, 0x19991000
	v_add_u32_e32 v145, s15, v0
	v_lshlrev_b64 v[132:133], 10, v[136:137]
	v_lshlrev_b64 v[130:131], 11, v[136:137]
	v_or_b32_e32 v0, s16, v142
	s_mov_b64 s[44:45], -1
	s_and_b64 vcc, exec, s[46:47]
	s_barrier
	s_cbranch_vccz .LBB0_496
	s_and_b64 vcc, exec, s[42:43]
	s_cbranch_vccz .LBB0_493
	s_and_b64 vcc, exec, s[62:63]
	s_cbranch_vccz .LBB0_490
	s_and_b64 vcc, exec, s[60:61]
	s_cbranch_vccz .LBB0_487
	s_and_b64 vcc, exec, s[58:59]
	s_cbranch_vccz .LBB0_484
	v_cmp_gt_u32_e32 vcc, s7, v0
	s_and_saveexec_b64 s[44:45], vcc
	s_cbranch_execz .LBB0_483
	v_mul_f32_e32 v137, 0xbfb8aa3b, v126
	v_exp_f32_e32 v137, v137
	v_mul_f32_e32 v143, 0xbfb8aa3b, v127
	v_exp_f32_e32 v143, v143
	v_mul_f32_e32 v147, 0xbfb8aa3b, v129
	v_add_f32_e32 v137, 1.0, v137
	v_rcp_f32_e32 v146, v137
	v_mul_f32_e32 v137, 0xbfb8aa3b, v128
	v_exp_f32_e32 v137, v137
	v_exp_f32_e32 v149, v147
	v_add_f32_e32 v143, 1.0, v143
	v_rcp_f32_e32 v147, v143
	v_add_f32_e32 v137, 1.0, v137
	v_mul_f32_e32 v143, 0xbfb8aa3b, v122
	v_rcp_f32_e32 v148, v137
	v_add_f32_e32 v137, 1.0, v149
	v_exp_f32_e32 v143, v143
	v_mul_f32_e32 v149, 0xbfb8aa3b, v123
	v_exp_f32_e32 v151, v149
	v_rcp_f32_e32 v149, v137
	v_add_f32_e32 v137, 1.0, v143
	v_mul_f32_e32 v143, 0xbfb8aa3b, v124
	v_rcp_f32_e32 v150, v137
	v_add_f32_e32 v137, 1.0, v151
	v_exp_f32_e32 v143, v143
	v_mul_f32_e32 v151, 0xbfb8aa3b, v125
	v_exp_f32_e32 v153, v151
	v_rcp_f32_e32 v151, v137
	v_add_f32_e32 v137, 1.0, v143
	v_rcp_f32_e32 v152, v137
	v_add_f32_e32 v137, 1.0, v153
	v_lshl_add_u64 v[154:155], s[34:35], 0, v[134:135]
	v_rcp_f32_e32 v153, v137
	v_lshl_add_u64 v[154:155], v[0:1], 2, v[154:155]
	v_add_co_u32_e32 v154, vcc, 0x438d000, v154
	s_nop 1
	v_addc_co_u32_e32 v155, vcc, 0, v155, vcc
	global_store_dwordx4 v[154:155], v[146:149], off
	global_store_dwordx4 v[154:155], v[150:153], off offset:16
